# further latency removals in light phases: gate-bias hoist and next-row prefetch in norm_gif, sliding-window sink load before the barrier, wave reductions of finalize and the four norm loops via DPP/pe
# baseline (speedup 1.0000x reference)
.LBB0_83:
	global_load_dwordx4 v[34:37], v[22:23], off offset:-4096
	global_load_dwordx4 v[8:11], v[22:23], off offset:-3072
	global_load_dwordx4 v[38:41], v[22:23], off offset:-2048
	global_load_dwordx4 v[4:7], v[22:23], off
	global_load_dwordx4 v[42:45], v[22:23], off offset:-1024
	global_load_dwordx4 v[46:49], v[22:23], off offset:1024
	global_load_dwordx4 v[0:3], v[22:23], off offset:3072
	global_load_dwordx4 v[50:53], v[22:23], off offset:2048
	global_load_dwordx4 v[54:57], v[12:13], off
	s_add_i32 s7, s7, s8
	v_lshl_add_u64 v[22:23], v[22:23], 0, s[2:3]
	s_cmpk_lt_i32 s7, 0x4000
	s_waitcnt vmcnt(8)
	v_mov_b32_e32 v60, v35
	s_waitcnt vmcnt(7)
	v_mov_b32_e32 v61, v9
	v_mov_b32_e32 v64, v37
	v_mov_b32_e32 v65, v11
	v_mov_b32_e32 v58, v34
	v_mov_b32_e32 v59, v8
	v_mov_b32_e32 v62, v36
	v_mov_b32_e32 v63, v10
	s_waitcnt vmcnt(6)
	v_pk_mul_f32 v[66:67], v[40:41], v[40:41]
	v_pk_mul_f32 v[68:69], v[38:39], v[38:39]
	v_pk_mul_f32 v[60:61], v[60:61], v[60:61]
	v_pk_mul_f32 v[64:65], v[64:65], v[64:65]
	v_pk_mov_b32 v[82:83], v[68:69], v[66:67] op_sel:[1,0]
	v_mov_b32_e32 v69, v67
	v_pk_fma_f32 v[58:59], v[58:59], v[58:59], v[60:61]
	v_pk_fma_f32 v[60:61], v[62:63], v[62:63], v[64:65]
	s_waitcnt vmcnt(4)
	v_mul_f32_e32 v70, v43, v43
	v_mul_f32_e32 v72, v45, v45
	v_pk_add_f32 v[62:63], v[82:83], v[68:69]
	v_pk_add_f32 v[58:59], v[58:59], v[60:61]
	v_mul_f32_e32 v81, v4, v4
	v_mul_f32_e32 v84, v5, v5
	v_mul_f32_e32 v85, v6, v6
	v_mul_f32_e32 v86, v7, v7
	v_pk_fma_f32 v[66:67], v[42:43], v[42:43], v[70:71] op_sel_hi:[1,1,0]
	v_pk_fma_f32 v[70:71], v[44:45], v[44:45], v[72:73] op_sel_hi:[1,1,0]
	v_pk_add_f32 v[60:61], v[62:63], v[62:63] op_sel:[0,1] op_sel_hi:[1,0]
	v_pk_add_f32 v[58:59], v[58:59], v[58:59] op_sel:[0,1] op_sel_hi:[1,0]
	s_waitcnt vmcnt(3)
	v_pk_mul_f32 v[74:75], v[48:49], v[48:49]
	v_pk_mul_f32 v[76:77], v[46:47], v[46:47]
	v_mov_b32_e32 v67, v85
	v_mov_b32_e32 v71, v86
	v_mov_b32_e32 v61, v84
	v_mov_b32_e32 v59, v81
	v_pk_mov_b32 v[72:73], v[76:77], v[74:75] op_sel:[1,0]
	v_mov_b32_e32 v77, v75
	v_pk_add_f32 v[62:63], v[66:67], v[70:71]
	v_pk_add_f32 v[58:59], v[58:59], v[60:61]
	s_waitcnt vmcnt(1)
	v_mul_f32_e32 v78, v51, v51
	v_mul_f32_e32 v80, v53, v53
	v_pk_add_f32 v[64:65], v[72:73], v[76:77]
	v_pk_add_f32 v[58:59], v[58:59], v[62:63]
	v_mul_f32_e32 v87, v0, v0
	v_mul_f32_e32 v88, v1, v1
	v_mul_f32_e32 v89, v2, v2
	v_mul_f32_e32 v90, v3, v3
	v_pk_fma_f32 v[74:75], v[50:51], v[50:51], v[78:79] op_sel_hi:[1,1,0]
	v_pk_fma_f32 v[78:79], v[52:53], v[52:53], v[80:81] op_sel_hi:[1,1,0]
	v_pk_add_f32 v[64:65], v[64:65], v[64:65] op_sel:[0,1] op_sel_hi:[1,0]
	v_pk_add_f32 v[58:59], v[58:59], v[58:59] op_sel:[0,1] op_sel_hi:[1,0]
	v_mov_b32_e32 v75, v89
	v_mov_b32_e32 v79, v90
	v_mov_b32_e32 v65, v88
	v_mov_b32_e32 v59, v87
	v_pk_add_f32 v[66:67], v[74:75], v[78:79]
	v_pk_add_f32 v[58:59], v[58:59], v[64:65]
	s_nop 0
	v_pk_add_f32 v[58:59], v[58:59], v[66:67]
	s_nop 0
	v_add_f32_e32 v58, v58, v59
	s_waitcnt lgkmcnt(0)
	s_nop 1
	v_add_f32_dpp v58, v58, v58 quad_perm:[1,0,3,2] row_mask:0xf bank_mask:0xf
	s_waitcnt lgkmcnt(0)
	s_nop 1
	v_add_f32_dpp v58, v58, v58 quad_perm:[2,3,0,1] row_mask:0xf bank_mask:0xf
	s_waitcnt lgkmcnt(0)
	s_nop 1
	v_add_f32_dpp v58, v58, v58 row_half_mirror row_mask:0xf bank_mask:0xf
	s_waitcnt lgkmcnt(0)
	s_nop 1
	v_add_f32_dpp v58, v58, v58 row_mirror row_mask:0xf bank_mask:0xf
	s_waitcnt lgkmcnt(0)
	v_mov_b32_e32 v59, v58
	s_nop 1
	v_permlane16_swap_b32_e32 v58, v59
	v_add_f32_e32 v58, v58, v59
	s_waitcnt lgkmcnt(0)
	v_mov_b32_e32 v59, v58
	s_nop 1
	v_permlane32_swap_b32_e32 v58, v59
	v_add_f32_e32 v58, v58, v59
	v_fmamk_f32 v58, v58, 0x3a000000, v32
	v_mul_f32_e32 v59, 0x4f800000, v58
	v_cmp_gt_f32_e32 vcc, s6, v58
	s_nop 1
	v_cndmask_b32_e32 v58, v58, v59, vcc
	v_sqrt_f32_e32 v59, v58
	s_nop 0
	v_add_u32_e32 v60, -1, v59
	v_add_u32_e32 v61, 1, v59
	v_fma_f32 v62, -v60, v59, v58
	v_fma_f32 v63, -v61, v59, v58
	v_cmp_ge_f32_e64 s[0:1], 0, v62
	s_nop 1
	v_cndmask_b32_e64 v59, v59, v60, s[0:1]
	v_cmp_lt_f32_e64 s[0:1], 0, v63
	s_nop 1
	v_cndmask_b32_e64 v59, v59, v61, s[0:1]
	v_mul_f32_e32 v60, 0x37800000, v59
	v_cndmask_b32_e32 v59, v59, v60, vcc
	v_cmp_class_f32_e32 vcc, v58, v33
	s_nop 1
	v_cndmask_b32_e32 v58, v59, v58, vcc
	v_div_scale_f32 v59, s[0:1], v58, v58, 1.0
	v_rcp_f32_e32 v61, v59
	v_div_scale_f32 v60, vcc, 1.0, v58, 1.0
	v_fma_f32 v62, -v59, v61, 1.0
	v_fmac_f32_e32 v61, v62, v61
	v_mul_f32_e32 v62, v60, v61
	v_fma_f32 v63, -v59, v62, v60
	v_fmac_f32_e32 v62, v63, v61
	v_fma_f32 v59, -v59, v62, v60
	v_div_fmas_f32 v59, v59, v61, v62
	v_div_fixup_f32 v58, v59, v58, 1.0
	v_pk_mul_f32 v[34:35], v[34:35], v[58:59] op_sel_hi:[1,0]
	v_pk_mul_f32 v[36:37], v[36:37], v[58:59] op_sel_hi:[1,0]
	s_waitcnt vmcnt(0)
	v_pk_mul_f32 v[34:35], v[54:55], v[34:35]
	v_pk_mul_f32 v[36:37], v[56:57], v[36:37]
	v_cvt_pk_bf16_f32 v34, v34, v35
	v_cvt_pk_bf16_f32 v35, v36, v37
	global_store_dwordx2 v[24:25], v[34:35], off
	v_pk_mul_f32 v[8:9], v[8:9], v[58:59] op_sel_hi:[1,0]
	v_pk_mul_f32 v[10:11], v[10:11], v[58:59] op_sel_hi:[1,0]
	v_pk_mul_f32 v[4:5], v[4:5], v[58:59] op_sel_hi:[1,0]
	v_pk_mul_f32 v[6:7], v[6:7], v[58:59] op_sel_hi:[1,0]
	v_pk_mul_f32 v[0:1], v[0:1], v[58:59] op_sel_hi:[1,0]
	v_pk_mul_f32 v[2:3], v[2:3], v[58:59] op_sel_hi:[1,0]
	v_pk_mul_f32 v[10:11], v[134:135], v[10:11]
	v_pk_mul_f32 v[8:9], v[132:133], v[8:9]
	v_pk_mul_f32 v[34:35], v[38:39], v[58:59] op_sel_hi:[1,0]
	v_cvt_pk_bf16_f32 v8, v8, v9
	v_cvt_pk_bf16_f32 v9, v10, v11
	global_store_dwordx2 v[24:25], v[8:9], off offset:512
	v_pk_mul_f32 v[36:37], v[40:41], v[58:59] op_sel_hi:[1,0]
	v_pk_mul_f32 v[8:9], v[136:137], v[34:35]
	v_pk_mul_f32 v[10:11], v[138:139], v[36:37]
	v_cvt_pk_bf16_f32 v8, v8, v9
	v_cvt_pk_bf16_f32 v9, v10, v11
	global_store_dwordx2 v[24:25], v[8:9], off offset:1024
	v_pk_mul_f32 v[34:35], v[42:43], v[58:59] op_sel_hi:[1,0]
	v_pk_mul_f32 v[36:37], v[44:45], v[58:59] op_sel_hi:[1,0]
	v_pk_mul_f32 v[8:9], v[140:141], v[34:35]
	v_pk_mul_f32 v[10:11], v[142:143], v[36:37]
	v_cvt_pk_bf16_f32 v8, v8, v9
	v_cvt_pk_bf16_f32 v9, v10, v11
	global_store_dwordx2 v[24:25], v[8:9], off offset:1536
	v_pk_mul_f32 v[6:7], v[146:147], v[6:7]
	v_pk_mul_f32 v[4:5], v[144:145], v[4:5]
	v_pk_mul_f32 v[8:9], v[46:47], v[58:59] op_sel_hi:[1,0]
	v_cvt_pk_bf16_f32 v4, v4, v5
	v_cvt_pk_bf16_f32 v5, v6, v7
	global_store_dwordx2 v[24:25], v[4:5], off offset:2048
	v_pk_mul_f32 v[10:11], v[48:49], v[58:59] op_sel_hi:[1,0]
	v_pk_mul_f32 v[4:5], v[148:149], v[8:9]
	v_pk_mul_f32 v[6:7], v[150:151], v[10:11]
	v_cvt_pk_bf16_f32 v4, v4, v5
	v_cvt_pk_bf16_f32 v5, v6, v7
	global_store_dwordx2 v[24:25], v[4:5], off offset:2560
	v_pk_mul_f32 v[8:9], v[50:51], v[58:59] op_sel_hi:[1,0]
	v_pk_mul_f32 v[10:11], v[52:53], v[58:59] op_sel_hi:[1,0]
	v_pk_mul_f32 v[4:5], v[8:9], v[152:153]
	v_pk_mul_f32 v[6:7], v[10:11], v[154:155]
	v_cvt_pk_bf16_f32 v4, v4, v5
	v_cvt_pk_bf16_f32 v5, v6, v7
	global_store_dwordx2 v[24:25], v[4:5], off offset:3072
	v_pk_mul_f32 v[2:3], v[2:3], v[158:159]
	v_pk_mul_f32 v[0:1], v[0:1], v[156:157]
	s_nop 0
	v_cvt_pk_bf16_f32 v0, v0, v1
	v_cvt_pk_bf16_f32 v1, v2, v3
	global_store_dwordx2 v[24:25], v[0:1], off offset:3584
	v_lshl_add_u64 v[24:25], v[24:25], 0, s[4:5]
	s_cbranch_scc1 .LBB0_83
	v_writelane_b32 v255, s8, 23
	s_nop 1
	v_writelane_b32 v255, s9, 24

.LBB0_438:
	global_load_dwordx4 v[34:37], v[22:23], off offset:-4096
	global_load_dwordx4 v[8:11], v[22:23], off offset:-3072
	global_load_dwordx4 v[38:41], v[22:23], off offset:-2048
	global_load_dwordx4 v[4:7], v[22:23], off
	global_load_dwordx4 v[42:45], v[22:23], off offset:-1024
	global_load_dwordx4 v[46:49], v[22:23], off offset:1024
	global_load_dwordx4 v[0:3], v[22:23], off offset:3072
	global_load_dwordx4 v[50:53], v[22:23], off offset:2048
	global_load_dwordx4 v[54:57], v[12:13], off
	s_add_i32 s7, s7, s10
	v_lshl_add_u64 v[22:23], v[22:23], 0, s[2:3]
	s_cmpk_lt_i32 s7, 0x4000
	s_waitcnt vmcnt(0)
	v_mov_b32_e32 v60, v35
	v_mov_b32_e32 v61, v9
	v_mov_b32_e32 v64, v37
	v_mov_b32_e32 v65, v11
	v_mov_b32_e32 v58, v34
	v_mov_b32_e32 v59, v8
	v_mov_b32_e32 v62, v36
	v_mov_b32_e32 v63, v10
	v_pk_mul_f32 v[66:67], v[40:41], v[40:41]
	v_pk_mul_f32 v[68:69], v[38:39], v[38:39]
	v_pk_mul_f32 v[60:61], v[60:61], v[60:61]
	v_pk_mul_f32 v[64:65], v[64:65], v[64:65]
	v_pk_mov_b32 v[82:83], v[68:69], v[66:67] op_sel:[1,0]
	v_mov_b32_e32 v69, v67
	v_pk_fma_f32 v[58:59], v[58:59], v[58:59], v[60:61]
	v_pk_fma_f32 v[60:61], v[62:63], v[62:63], v[64:65]
	v_mul_f32_e32 v70, v43, v43
	v_mul_f32_e32 v72, v45, v45
	v_pk_add_f32 v[62:63], v[82:83], v[68:69]
	v_pk_add_f32 v[58:59], v[58:59], v[60:61]
	v_mul_f32_e32 v81, v4, v4
	v_mul_f32_e32 v84, v5, v5
	v_mul_f32_e32 v85, v6, v6
	v_mul_f32_e32 v86, v7, v7
	v_pk_fma_f32 v[66:67], v[42:43], v[42:43], v[70:71] op_sel_hi:[1,1,0]
	v_pk_fma_f32 v[70:71], v[44:45], v[44:45], v[72:73] op_sel_hi:[1,1,0]
	v_pk_add_f32 v[60:61], v[62:63], v[62:63] op_sel:[0,1] op_sel_hi:[1,0]
	v_pk_add_f32 v[58:59], v[58:59], v[58:59] op_sel:[0,1] op_sel_hi:[1,0]
	v_pk_mul_f32 v[74:75], v[48:49], v[48:49]
	v_pk_mul_f32 v[76:77], v[46:47], v[46:47]
	v_mov_b32_e32 v67, v85
	v_mov_b32_e32 v71, v86
	v_mov_b32_e32 v61, v84
	v_mov_b32_e32 v59, v81
	v_pk_mov_b32 v[72:73], v[76:77], v[74:75] op_sel:[1,0]
	v_mov_b32_e32 v77, v75
	v_pk_add_f32 v[62:63], v[66:67], v[70:71]
	v_pk_add_f32 v[58:59], v[58:59], v[60:61]
	v_mul_f32_e32 v78, v51, v51
	v_mul_f32_e32 v80, v53, v53
	v_pk_add_f32 v[64:65], v[72:73], v[76:77]
	v_pk_add_f32 v[58:59], v[58:59], v[62:63]
	v_mul_f32_e32 v87, v0, v0
	v_mul_f32_e32 v88, v1, v1
	v_mul_f32_e32 v89, v2, v2
	v_mul_f32_e32 v90, v3, v3
	v_pk_fma_f32 v[74:75], v[50:51], v[50:51], v[78:79] op_sel_hi:[1,1,0]
	v_pk_fma_f32 v[78:79], v[52:53], v[52:53], v[80:81] op_sel_hi:[1,1,0]
	v_pk_add_f32 v[64:65], v[64:65], v[64:65] op_sel:[0,1] op_sel_hi:[1,0]
	v_pk_add_f32 v[58:59], v[58:59], v[58:59] op_sel:[0,1] op_sel_hi:[1,0]
	v_mov_b32_e32 v75, v89
	v_mov_b32_e32 v79, v90
	v_mov_b32_e32 v65, v88
	v_mov_b32_e32 v59, v87
	v_pk_add_f32 v[66:67], v[74:75], v[78:79]
	v_pk_add_f32 v[58:59], v[58:59], v[64:65]
	s_nop 0
	v_pk_add_f32 v[58:59], v[58:59], v[66:67]
	s_nop 0
	v_add_f32_e32 v58, v58, v59
	s_waitcnt lgkmcnt(0)
	s_nop 1
	v_add_f32_dpp v58, v58, v58 quad_perm:[1,0,3,2] row_mask:0xf bank_mask:0xf
	s_waitcnt lgkmcnt(0)
	s_nop 1
	v_add_f32_dpp v58, v58, v58 quad_perm:[2,3,0,1] row_mask:0xf bank_mask:0xf
	s_waitcnt lgkmcnt(0)
	s_nop 1
	v_add_f32_dpp v58, v58, v58 row_half_mirror row_mask:0xf bank_mask:0xf
	s_waitcnt lgkmcnt(0)
	s_nop 1
	v_add_f32_dpp v58, v58, v58 row_mirror row_mask:0xf bank_mask:0xf
	s_waitcnt lgkmcnt(0)
	v_mov_b32_e32 v59, v58
	s_nop 1
	v_permlane16_swap_b32_e32 v58, v59
	v_add_f32_e32 v58, v58, v59
	s_waitcnt lgkmcnt(0)
	v_mov_b32_e32 v59, v58
	s_nop 1
	v_permlane32_swap_b32_e32 v58, v59
	v_add_f32_e32 v58, v58, v59
	v_fmamk_f32 v58, v58, 0x3a000000, v32
	v_mul_f32_e32 v59, 0x4f800000, v58
	v_cmp_gt_f32_e32 vcc, s6, v58
	s_nop 1
	v_cndmask_b32_e32 v58, v58, v59, vcc
	v_sqrt_f32_e32 v59, v58
	s_nop 0
	v_add_u32_e32 v60, -1, v59
	v_add_u32_e32 v61, 1, v59
	v_fma_f32 v62, -v60, v59, v58
	v_fma_f32 v63, -v61, v59, v58
	v_cmp_ge_f32_e64 s[0:1], 0, v62
	s_nop 1
	v_cndmask_b32_e64 v59, v59, v60, s[0:1]
	v_cmp_lt_f32_e64 s[0:1], 0, v63
	s_nop 1
	v_cndmask_b32_e64 v59, v59, v61, s[0:1]
	v_mul_f32_e32 v60, 0x37800000, v59
	v_cndmask_b32_e32 v59, v59, v60, vcc
	v_cmp_class_f32_e32 vcc, v58, v33
	s_nop 1
	v_cndmask_b32_e32 v58, v59, v58, vcc
	v_div_scale_f32 v59, s[0:1], v58, v58, 1.0
	v_rcp_f32_e32 v61, v59
	v_div_scale_f32 v60, vcc, 1.0, v58, 1.0
	v_fma_f32 v62, -v59, v61, 1.0
	v_fmac_f32_e32 v61, v62, v61
	v_mul_f32_e32 v62, v60, v61
	v_fma_f32 v63, -v59, v62, v60
	v_fmac_f32_e32 v62, v63, v61
	v_fma_f32 v59, -v59, v62, v60
	v_div_fmas_f32 v59, v59, v61, v62
	v_div_fixup_f32 v58, v59, v58, 1.0
	v_pk_mul_f32 v[34:35], v[34:35], v[58:59] op_sel_hi:[1,0]
	v_pk_mul_f32 v[36:37], v[36:37], v[58:59] op_sel_hi:[1,0]
	v_pk_mul_f32 v[34:35], v[54:55], v[34:35]
	v_pk_mul_f32 v[36:37], v[56:57], v[36:37]
	v_cvt_pk_bf16_f32 v34, v34, v35
	v_cvt_pk_bf16_f32 v35, v36, v37
	global_store_dwordx2 v[24:25], v[34:35], off
	v_pk_mul_f32 v[8:9], v[8:9], v[58:59] op_sel_hi:[1,0]
	v_pk_mul_f32 v[10:11], v[10:11], v[58:59] op_sel_hi:[1,0]
	v_pk_mul_f32 v[4:5], v[4:5], v[58:59] op_sel_hi:[1,0]
	v_pk_mul_f32 v[6:7], v[6:7], v[58:59] op_sel_hi:[1,0]
	v_pk_mul_f32 v[0:1], v[0:1], v[58:59] op_sel_hi:[1,0]
	v_pk_mul_f32 v[2:3], v[2:3], v[58:59] op_sel_hi:[1,0]
	v_pk_mul_f32 v[10:11], v[134:135], v[10:11]
	v_pk_mul_f32 v[8:9], v[132:133], v[8:9]
	v_pk_mul_f32 v[34:35], v[38:39], v[58:59] op_sel_hi:[1,0]
	v_cvt_pk_bf16_f32 v8, v8, v9
	v_cvt_pk_bf16_f32 v9, v10, v11
	global_store_dwordx2 v[24:25], v[8:9], off offset:512
	v_pk_mul_f32 v[36:37], v[40:41], v[58:59] op_sel_hi:[1,0]
	v_pk_mul_f32 v[8:9], v[136:137], v[34:35]
	v_pk_mul_f32 v[10:11], v[138:139], v[36:37]
	v_cvt_pk_bf16_f32 v8, v8, v9
	v_cvt_pk_bf16_f32 v9, v10, v11
	global_store_dwordx2 v[24:25], v[8:9], off offset:1024
	v_pk_mul_f32 v[34:35], v[42:43], v[58:59] op_sel_hi:[1,0]
	v_pk_mul_f32 v[36:37], v[44:45], v[58:59] op_sel_hi:[1,0]
	v_pk_mul_f32 v[8:9], v[140:141], v[34:35]
	v_pk_mul_f32 v[10:11], v[142:143], v[36:37]
	v_cvt_pk_bf16_f32 v8, v8, v9
	v_cvt_pk_bf16_f32 v9, v10, v11
	global_store_dwordx2 v[24:25], v[8:9], off offset:1536
	v_pk_mul_f32 v[6:7], v[146:147], v[6:7]
	v_pk_mul_f32 v[4:5], v[144:145], v[4:5]
	v_pk_mul_f32 v[8:9], v[46:47], v[58:59] op_sel_hi:[1,0]
	v_cvt_pk_bf16_f32 v4, v4, v5
	v_cvt_pk_bf16_f32 v5, v6, v7
	global_store_dwordx2 v[24:25], v[4:5], off offset:2048
	v_pk_mul_f32 v[10:11], v[48:49], v[58:59] op_sel_hi:[1,0]
	v_pk_mul_f32 v[4:5], v[148:149], v[8:9]
	v_pk_mul_f32 v[6:7], v[150:151], v[10:11]
	v_cvt_pk_bf16_f32 v4, v4, v5
	v_cvt_pk_bf16_f32 v5, v6, v7
	global_store_dwordx2 v[24:25], v[4:5], off offset:2560
	v_pk_mul_f32 v[8:9], v[50:51], v[58:59] op_sel_hi:[1,0]
	v_pk_mul_f32 v[10:11], v[52:53], v[58:59] op_sel_hi:[1,0]
	v_pk_mul_f32 v[4:5], v[8:9], v[152:153]
	v_pk_mul_f32 v[6:7], v[10:11], v[154:155]
	v_cvt_pk_bf16_f32 v4, v4, v5
	v_cvt_pk_bf16_f32 v5, v6, v7
	global_store_dwordx2 v[24:25], v[4:5], off offset:3072
	v_pk_mul_f32 v[2:3], v[2:3], v[158:159]
	v_pk_mul_f32 v[0:1], v[0:1], v[156:157]
	s_nop 0
	v_cvt_pk_bf16_f32 v0, v0, v1
	v_cvt_pk_bf16_f32 v1, v2, v3
	global_store_dwordx2 v[24:25], v[0:1], off offset:3584
	v_lshl_add_u64 v[24:25], v[24:25], 0, s[4:5]
	s_cbranch_scc1 .LBB0_438

.LBB0_656:
	s_or_b64 exec, exec, s[6:7]
	v_add_u32_e32 v80, s11, v102
	v_lshlrev_b64 v[12:13], 7, v[80:81]
	v_add_u32_e32 v80, s11, v104
	v_lshlrev_b64 v[20:21], 7, v[80:81]
	v_lshl_add_u64 v[14:15], v[10:11], 0, v[12:13]
	v_lshl_add_u64 v[16:17], v[8:9], 0, v[12:13]
	v_lshl_add_u64 v[22:23], v[10:11], 0, v[20:21]
	v_lshl_add_u64 v[8:9], v[8:9], 0, v[20:21]
	global_load_dwordx4 v[12:15], v[14:15], off
	s_nop 0
	global_load_dwordx4 v[16:19], v[16:17], off
	s_nop 0
	global_load_dwordx4 v[8:11], v[8:9], off
	s_nop 0
	global_load_dwordx4 v[20:23], v[22:23], off
	s_lshr_b32 s9, s9, 6
	s_lshl_b32 s6, s8, 3
	s_add_i32 s7, s9, s6
	s_lshl_b32 s6, s7, 2
	s_waitcnt vmcnt(5)
	ds_write_b128 v124, v[4:7]
	s_waitcnt vmcnt(4)
	ds_write_b128 v125, v[0:3] offset:32768
	v_add_u32_e32 v0, v93, v103
	v_mov_b32_e32 v2, s6
	global_load_dword v133, v2, s[68:69]
	v_add_u32_e32 v1, v100, v103
	s_lshl_b32 s6, s0, 5
	s_add_i32 s6, s7, s6
	v_lshl_or_b32 v96, s7, 6, v113
	s_ashr_i32 s7, s6, 31
	s_lshl_b64 s[6:7], s[6:7], 20
	s_add_u32 s6, s96, s6
	s_addc_u32 s7, s88, s7
	s_lshl_b32 s8, s10, 7
	s_add_u32 s6, s6, s8
	s_addc_u32 s7, s7, 0
	v_mov_b32_e32 v95, v81
	s_cmp_lg_u32 s1, 0
	v_lshl_add_u64 v[98:99], s[6:7], 0, v[94:95]
	s_cselect_b64 s[18:19], -1, 0
	s_ashr_i32 s1, s0, 31
	s_lshl_b32 s6, s9, 13
	s_lshl_b64 s[20:21], s[0:1], 13
	s_add_i32 s0, s6, 0
	s_add_i32 s0, s0, 0x10000
	s_mov_b32 s25, 0
	v_mov_b32_e32 v97, v81
	s_and_b64 s[6:7], s[2:3], s[18:19]
	s_and_b64 s[8:9], s[4:5], s[18:19]
	s_or_b32 s20, s20, s10
	s_waitcnt vmcnt(3)
	ds_write_b128 v0, v[16:19]
	ds_write_b128 v1, v[12:15] offset:32768
	s_waitcnt vmcnt(2)
	ds_write_b128 v126, v[8:11]
	s_waitcnt vmcnt(1)
	ds_write_b128 v127, v[20:23] offset:32768
	s_waitcnt lgkmcnt(0)
	s_barrier
	v_lshl_add_u32 v1, v87, 2, s0
	v_lshl_add_u32 v2, v113, 2, s0
	v_add_u32_e32 v95, v1, v120
	v_add_u32_e32 v130, v2, v114
	v_add_u32_e32 v131, v2, v121
	v_add_u32_e32 v132, v2, v122
	v_add_u32_e32 v134, v2, v123
	s_waitcnt vmcnt(0)
	v_mul_f32_e32 v133, 0x3fb8aa3b, v133
	s_branch .LBB0_658

.LBB0_813:
	s_and_saveexec_b64 s[0:1], s[2:3]
	global_load_dword v204, v[34:35], off
	s_or_b64 exec, exec, s[0:1]
	global_load_dwordx4 v[112:115], v[36:37], off offset:1024
	global_load_dwordx4 v[116:119], v[36:37], off offset:2048
	global_load_dwordx4 v[120:123], v[36:37], off offset:3072
	global_load_dwordx4 v[124:127], v[38:39], off
	global_load_dwordx4 v[128:131], v[40:41], off
	global_load_dwordx4 v[132:135], v[42:43], off
	global_load_dwordx4 v[136:139], v[44:45], off
	s_lshl_b32 s29, s28, 6
	s_mov_b32 s30, 0
	s_branch .LBB0_815

.LBB0_815:
	s_add_i32 s31, s30, s17
	s_add_i32 s0, s31, s29
	s_ashr_i32 s1, s0, 31
	s_cmp_eq_u32 s30, 0
	s_cbranch_scc0 .Lmy_p8_copy
	s_lshl_b64 s[34:35], s[0:1], 13
	v_lshl_add_u64 v[0:1], v[30:31], 0, s[34:35]
	global_load_dwordx4 v[46:49], v[0:1], off
	global_load_dwordx4 v[8:11], v[0:1], off offset:1024
	global_load_dwordx4 v[24:27], v[0:1], off offset:2048
	global_load_dwordx4 v[16:19], v[0:1], off offset:3072
	v_add_co_u32_e32 v12, vcc, s18, v0
	s_lshl_b64 s[34:35], s[0:1], 12
	s_nop 0
	v_addc_co_u32_e32 v13, vcc, 0, v1, vcc
	global_load_dwordx4 v[4:7], v[12:13], off
	global_load_dwordx4 v[20:23], v[12:13], off offset:1024
	global_load_dwordx4 v[0:3], v[12:13], off offset:3072
	s_nop 0
	global_load_dwordx4 v[12:15], v[12:13], off offset:2048
	s_nop 0
	global_load_dwordx4 v[70:73], v[36:37], off
	s_branch .Lmy_p8_go
.Lmy_p8_copy:
	s_lshl_b64 s[34:35], s[0:1], 12
	s_waitcnt vmcnt(0)
	v_mov_b64_e32 v[46:47], v[140:141]
	v_mov_b64_e32 v[48:49], v[142:143]
	v_mov_b64_e32 v[8:9], v[144:145]
	v_mov_b64_e32 v[10:11], v[146:147]
	v_mov_b64_e32 v[24:25], v[148:149]
	v_mov_b64_e32 v[26:27], v[150:151]
	v_mov_b64_e32 v[16:17], v[152:153]
	v_mov_b64_e32 v[18:19], v[154:155]
	v_mov_b64_e32 v[4:5], v[156:157]
	v_mov_b64_e32 v[6:7], v[158:159]
	v_mov_b64_e32 v[20:21], v[160:161]
	v_mov_b64_e32 v[22:23], v[162:163]
	v_mov_b64_e32 v[0:1], v[164:165]
	v_mov_b64_e32 v[2:3], v[166:167]
	v_mov_b64_e32 v[12:13], v[168:169]
	v_mov_b64_e32 v[14:15], v[170:171]
	global_load_dwordx4 v[70:73], v[36:37], off
.Lmy_p8_go:
	s_waitcnt vmcnt(8)
	v_mov_b32_e32 v76, v47
	s_waitcnt vmcnt(7)
	v_mov_b32_e32 v77, v9
	v_mov_b32_e32 v80, v49
	v_mov_b32_e32 v81, v11
	v_mov_b32_e32 v74, v46
	v_mov_b32_e32 v75, v8
	v_mov_b32_e32 v78, v48
	v_mov_b32_e32 v79, v10
	s_waitcnt vmcnt(6)
	v_pk_mul_f32 v[82:83], v[26:27], v[26:27]
	v_pk_mul_f32 v[84:85], v[24:25], v[24:25]
	v_pk_mul_f32 v[76:77], v[76:77], v[76:77]
	v_pk_mul_f32 v[80:81], v[80:81], v[80:81]
	v_pk_mov_b32 v[90:91], v[84:85], v[82:83] op_sel:[1,0]
	v_mov_b32_e32 v85, v83
	v_pk_fma_f32 v[74:75], v[74:75], v[74:75], v[76:77]
	v_pk_fma_f32 v[76:77], v[78:79], v[78:79], v[80:81]
	s_waitcnt vmcnt(5)
	v_mul_f32_e32 v86, v17, v17
	v_mul_f32_e32 v88, v19, v19
	v_pk_add_f32 v[78:79], v[90:91], v[84:85]
	v_pk_add_f32 v[74:75], v[74:75], v[76:77]
	s_waitcnt vmcnt(4)
	v_mul_f32_e32 v95, v4, v4
	v_mul_f32_e32 v97, v5, v5
	v_mul_f32_e32 v98, v6, v6
	v_mul_f32_e32 v99, v7, v7
	v_pk_fma_f32 v[82:83], v[16:17], v[16:17], v[86:87] op_sel_hi:[1,1,0]
	v_pk_fma_f32 v[86:87], v[18:19], v[18:19], v[88:89] op_sel_hi:[1,1,0]
	v_pk_add_f32 v[76:77], v[78:79], v[78:79] op_sel:[0,1] op_sel_hi:[1,0]
	v_pk_add_f32 v[74:75], v[74:75], v[74:75] op_sel:[0,1] op_sel_hi:[1,0]
	s_waitcnt vmcnt(3)
	v_pk_mul_f32 v[88:89], v[22:23], v[22:23]
	v_pk_mul_f32 v[92:93], v[20:21], v[20:21]
	v_mov_b32_e32 v83, v98
	v_mov_b32_e32 v87, v99
	v_mov_b32_e32 v77, v97
	v_mov_b32_e32 v75, v95
	v_pk_mov_b32 v[80:81], v[92:93], v[88:89] op_sel:[1,0]
	v_mov_b32_e32 v93, v89
	v_pk_add_f32 v[78:79], v[82:83], v[86:87]
	v_pk_add_f32 v[74:75], v[74:75], v[76:77]
	s_waitcnt vmcnt(1)
	v_mul_f32_e32 v94, v13, v13
	v_mul_f32_e32 v96, v15, v15
	v_pk_add_f32 v[80:81], v[80:81], v[92:93]
	v_pk_add_f32 v[74:75], v[74:75], v[78:79]
	v_mul_f32_e32 v100, v0, v0
	v_mul_f32_e32 v101, v1, v1
	v_mul_f32_e32 v102, v2, v2
	v_mul_f32_e32 v103, v3, v3
	v_pk_fma_f32 v[84:85], v[12:13], v[12:13], v[94:95] op_sel_hi:[1,1,0]
	v_pk_fma_f32 v[88:89], v[14:15], v[14:15], v[96:97] op_sel_hi:[1,1,0]
	v_pk_add_f32 v[80:81], v[80:81], v[80:81] op_sel:[0,1] op_sel_hi:[1,0]
	v_pk_add_f32 v[74:75], v[74:75], v[74:75] op_sel:[0,1] op_sel_hi:[1,0]
	v_mov_b32_e32 v85, v102
	v_mov_b32_e32 v89, v103
	v_mov_b32_e32 v81, v101
	v_mov_b32_e32 v75, v100
	v_pk_add_f32 v[82:83], v[84:85], v[88:89]
	v_pk_add_f32 v[74:75], v[74:75], v[80:81]
	s_nop 0
	v_pk_add_f32 v[74:75], v[74:75], v[82:83]
	s_nop 0
	v_add_f32_e32 v74, v74, v75
	s_waitcnt lgkmcnt(0)
	s_nop 1
	v_add_f32_dpp v74, v74, v74 quad_perm:[1,0,3,2] row_mask:0xf bank_mask:0xf
	s_waitcnt lgkmcnt(0)
	s_nop 1
	v_add_f32_dpp v74, v74, v74 quad_perm:[2,3,0,1] row_mask:0xf bank_mask:0xf
	s_waitcnt lgkmcnt(0)
	s_nop 1
	v_add_f32_dpp v74, v74, v74 row_half_mirror row_mask:0xf bank_mask:0xf
	s_waitcnt lgkmcnt(0)
	s_nop 1
	v_add_f32_dpp v74, v74, v74 row_mirror row_mask:0xf bank_mask:0xf
	s_waitcnt lgkmcnt(0)
	v_mov_b32_e32 v75, v74
	s_nop 1
	v_permlane16_swap_b32_e32 v74, v75
	v_add_f32_e32 v74, v74, v75
	s_waitcnt lgkmcnt(0)
	v_mov_b32_e32 v75, v74
	s_nop 1
	v_permlane32_swap_b32_e32 v74, v75
	v_add_f32_e32 v74, v74, v75
	v_fmamk_f32 v74, v74, 0x3a000000, v66
	v_mul_f32_e32 v75, 0x4f800000, v74
	v_cmp_gt_f32_e32 vcc, s19, v74
	s_nop 1
	v_cndmask_b32_e32 v74, v74, v75, vcc
	v_sqrt_f32_e32 v75, v74
	s_nop 0
	v_add_u32_e32 v76, -1, v75
	v_add_u32_e32 v77, 1, v75
	v_fma_f32 v78, -v76, v75, v74
	v_fma_f32 v79, -v77, v75, v74
	v_cmp_ge_f32_e64 s[0:1], 0, v78
	s_nop 1
	v_cndmask_b32_e64 v75, v75, v76, s[0:1]
	v_cmp_lt_f32_e64 s[0:1], 0, v79
	s_nop 1
	v_cndmask_b32_e64 v75, v75, v77, s[0:1]
	v_mul_f32_e32 v76, 0x37800000, v75
	v_cndmask_b32_e32 v75, v75, v76, vcc
	v_cmp_class_f32_e32 vcc, v74, v67
	v_lshl_add_u64 v[76:77], v[32:33], 0, s[34:35]
	s_nop 0
	v_cndmask_b32_e32 v74, v75, v74, vcc
	v_div_scale_f32 v75, s[0:1], v74, v74, 1.0
	v_rcp_f32_e32 v78, v75
	v_div_scale_f32 v79, vcc, 1.0, v74, 1.0
	s_mov_b32 s0, 0
	v_fma_f32 v80, -v75, v78, 1.0
	v_fmac_f32_e32 v78, v80, v78
	v_mul_f32_e32 v80, v79, v78
	v_fma_f32 v81, -v75, v80, v79
	v_fmac_f32_e32 v80, v81, v78
	v_fma_f32 v75, -v75, v80, v79
	v_div_fmas_f32 v75, v75, v78, v80
	v_div_fixup_f32 v78, v75, v74, 1.0
	v_pk_mul_f32 v[46:47], v[46:47], v[78:79] op_sel_hi:[1,0]
	v_pk_mul_f32 v[48:49], v[48:49], v[78:79] op_sel_hi:[1,0]
	s_waitcnt vmcnt(0)
	v_pk_mul_f32 v[82:83], v[70:71], v[46:47]
	v_pk_mul_f32 v[80:81], v[72:73], v[48:49]
	v_cvt_pk_bf16_f32 v46, v82, v83
	v_cvt_pk_bf16_f32 v47, v80, v81
	global_store_dwordx2 v[76:77], v[46:47], off
	v_pk_mul_f32 v[70:71], v[8:9], v[78:79] op_sel_hi:[1,0]
	v_pk_mul_f32 v[8:9], v[10:11], v[78:79] op_sel_hi:[1,0]
	v_pk_mul_f32 v[26:27], v[26:27], v[78:79] op_sel_hi:[1,0]
	v_pk_mul_f32 v[24:25], v[24:25], v[78:79] op_sel_hi:[1,0]
	v_pk_mul_f32 v[18:19], v[18:19], v[78:79] op_sel_hi:[1,0]
	v_pk_mul_f32 v[16:17], v[16:17], v[78:79] op_sel_hi:[1,0]
	v_pk_mul_f32 v[22:23], v[22:23], v[78:79] op_sel_hi:[1,0]
	v_pk_mul_f32 v[20:21], v[20:21], v[78:79] op_sel_hi:[1,0]
	v_pk_mul_f32 v[14:15], v[14:15], v[78:79] op_sel_hi:[1,0]
	v_pk_mul_f32 v[12:13], v[12:13], v[78:79] op_sel_hi:[1,0]
	v_pk_mul_f32 v[8:9], v[114:115], v[8:9]
	v_pk_mul_f32 v[10:11], v[112:113], v[70:71]
	v_cvt_pk_bf16_f32 v47, v8, v9
	v_cvt_pk_bf16_f32 v46, v10, v11
	global_store_dwordx2 v[76:77], v[46:47], off offset:512
	v_pk_mul_f32 v[70:71], v[4:5], v[78:79] op_sel_hi:[1,0]
	v_pk_mul_f32 v[4:5], v[6:7], v[78:79] op_sel_hi:[1,0]
	v_pk_mul_f32 v[24:25], v[116:117], v[24:25]
	v_pk_mul_f32 v[26:27], v[118:119], v[26:27]
	v_cvt_pk_bf16_f32 v46, v24, v25
	v_cvt_pk_bf16_f32 v47, v26, v27
	global_store_dwordx2 v[76:77], v[46:47], off offset:1024
	v_pk_mul_f32 v[16:17], v[120:121], v[16:17]
	v_pk_mul_f32 v[18:19], v[122:123], v[18:19]
	v_cvt_pk_bf16_f32 v46, v16, v17
	v_cvt_pk_bf16_f32 v47, v18, v19
	global_store_dwordx2 v[76:77], v[46:47], off offset:1536
	v_pk_mul_f32 v[4:5], v[126:127], v[4:5]
	v_pk_mul_f32 v[6:7], v[124:125], v[70:71]
	v_cvt_pk_bf16_f32 v47, v4, v5
	v_cvt_pk_bf16_f32 v46, v6, v7
	global_store_dwordx2 v[76:77], v[46:47], off offset:2048
	v_mov_b32_e32 v70, 0
	v_pk_mul_f32 v[20:21], v[128:129], v[20:21]
	v_pk_mul_f32 v[22:23], v[130:131], v[22:23]
	v_cvt_pk_bf16_f32 v46, v20, v21
	v_cvt_pk_bf16_f32 v47, v22, v23
	global_store_dwordx2 v[76:77], v[46:47], off offset:2560
	v_pk_mul_f32 v[12:13], v[12:13], v[132:133]
	v_pk_mul_f32 v[14:15], v[14:15], v[134:135]
	v_cvt_pk_bf16_f32 v46, v12, v13
	v_cvt_pk_bf16_f32 v47, v14, v15
	global_store_dwordx2 v[76:77], v[46:47], off offset:3072
	v_pk_mul_f32 v[48:49], v[0:1], v[78:79] op_sel_hi:[1,0]
	v_pk_mul_f32 v[46:47], v[2:3], v[78:79] op_sel_hi:[1,0]
	v_mov_b32_e32 v0, v82
	v_mov_b32_e32 v2, v80
	v_mov_b32_e32 v1, v10
	v_mov_b32_e32 v10, v83
	v_mov_b32_e32 v3, v8
	v_mov_b32_e32 v8, v81
	v_pk_mul_f32 v[46:47], v[46:47], v[138:139]
	v_pk_mul_f32 v[48:49], v[48:49], v[136:137]
	v_cvt_pk_bf16_f32 v73, v46, v47
	v_cvt_pk_bf16_f32 v72, v48, v49
	global_store_dwordx2 v[76:77], v[72:73], off offset:3584
	s_cmp_lt_u32 s30, 7
	s_cbranch_scc0 .Lmy_p8_nopf
	s_add_i32 s46, s31, s29
	s_add_i32 s46, s46, 1
	s_ashr_i32 s47, s46, 31
	s_lshl_b64 s[46:47], s[46:47], 13
	s_mov_b32 s68, s18
	s_mov_b32 s69, 0
	v_lshl_add_u64 v[172:173], v[30:31], 0, s[46:47]
	v_lshl_add_u64 v[174:175], v[172:173], 0, s[68:69]
	global_load_dwordx4 v[140:143], v[172:173], off
	global_load_dwordx4 v[144:147], v[172:173], off offset:1024
	global_load_dwordx4 v[148:151], v[172:173], off offset:2048
	global_load_dwordx4 v[152:155], v[172:173], off offset:3072
	global_load_dwordx4 v[156:159], v[174:175], off
	global_load_dwordx4 v[160:163], v[174:175], off offset:1024
	global_load_dwordx4 v[164:167], v[174:175], off offset:3072
	global_load_dwordx4 v[168:171], v[174:175], off offset:2048
.Lmy_p8_nopf:
.LBB0_816:
	v_add_u32_e32 v71, s0, v57
	ds_read_b128 v[72:75], v71
	ds_read_b128 v[76:79], v71 offset:1024
	ds_read_b128 v[80:83], v71 offset:2048
	ds_read_b128 v[84:87], v71 offset:3072
	ds_read_b128 v[88:91], v71 offset:4096
	ds_read_b128 v[92:95], v71 offset:5120
	ds_read_b128 v[96:99], v71 offset:6144
	ds_read_b128 v[100:103], v71 offset:7168
	s_waitcnt lgkmcnt(6)
	v_mov_b32_e32 v105, v76
	v_mov_b32_e32 v76, v73
	v_mov_b32_e32 v73, v78
	v_mov_b32_e32 v78, v75
	v_mov_b32_e32 v104, v72
	v_mov_b32_e32 v72, v74
	s_waitcnt lgkmcnt(5)
	v_pk_mul_f32 v[74:75], v[26:27], v[82:83]
	v_pk_mul_f32 v[80:81], v[24:25], v[80:81]
	v_pk_mul_f32 v[76:77], v[10:11], v[76:77]
	v_pk_mul_f32 v[78:79], v[8:9], v[78:79]
	s_waitcnt lgkmcnt(0)
	v_mul_f32_e32 v108, v46, v102
	v_mul_f32_e32 v109, v47, v103
	v_pk_mov_b32 v[102:103], v[80:81], v[74:75] op_sel:[1,0]
	v_mov_b32_e32 v81, v75
	v_pk_fma_f32 v[76:77], v[0:1], v[104:105], v[76:77]
	v_pk_fma_f32 v[72:73], v[2:3], v[72:73], v[78:79]
	v_mul_f32_e32 v83, v6, v88
	v_mul_f32_e32 v82, v17, v85
	v_mul_f32_e32 v88, v19, v87
	v_pk_add_f32 v[78:79], v[102:103], v[80:81]
	v_pk_add_f32 v[72:73], v[76:77], v[72:73]
	v_mul_f32_e32 v71, v7, v89
	v_mul_f32_e32 v106, v4, v90
	v_mul_f32_e32 v107, v5, v91
	v_pk_fma_f32 v[74:75], v[16:17], v[84:85], v[82:83] op_sel_hi:[1,1,0]
	v_pk_fma_f32 v[84:85], v[18:19], v[86:87], v[88:89] op_sel_hi:[1,1,0]
	v_pk_add_f32 v[76:77], v[78:79], v[78:79] op_sel:[0,1] op_sel_hi:[1,0]
	v_add_f32_e32 v72, 0, v72
	v_pk_mul_f32 v[90:91], v[22:23], v[94:95]
	v_pk_mul_f32 v[92:93], v[20:21], v[92:93]
	v_mov_b32_e32 v75, v106
	v_mov_b32_e32 v85, v107
	v_mov_b32_e32 v77, v71
	v_add_f32_e32 v82, v72, v73
	v_pk_mov_b32 v[86:87], v[92:93], v[90:91] op_sel:[1,0]
	v_mov_b32_e32 v93, v91
	v_pk_add_f32 v[74:75], v[74:75], v[84:85]
	v_pk_add_f32 v[72:73], v[82:83], v[76:77]
	v_mul_f32_e32 v95, v48, v100
	v_mul_f32_e32 v101, v49, v101
	v_mul_f32_e32 v94, v13, v97
	v_mul_f32_e32 v100, v15, v99
	v_pk_add_f32 v[80:81], v[86:87], v[92:93]
	v_pk_add_f32 v[72:73], v[72:73], v[74:75]
	v_pk_fma_f32 v[88:89], v[12:13], v[96:97], v[94:95] op_sel_hi:[1,1,0]
	v_pk_fma_f32 v[90:91], v[14:15], v[98:99], v[100:101] op_sel_hi:[1,1,0]
	v_pk_add_f32 v[78:79], v[80:81], v[80:81] op_sel:[0,1] op_sel_hi:[1,0]
	v_pk_add_f32 v[72:73], v[72:73], v[72:73] op_sel:[0,1] op_sel_hi:[1,0]
	v_mov_b32_e32 v89, v108
	v_mov_b32_e32 v91, v109
	v_mov_b32_e32 v79, v101
	v_mov_b32_e32 v73, v95
	v_pk_add_f32 v[80:81], v[88:89], v[90:91]
	v_pk_add_f32 v[72:73], v[72:73], v[78:79]
	v_cmp_eq_u32_e32 vcc, s0, v65
	v_pk_add_f32 v[72:73], v[72:73], v[80:81]
	s_addk_i32 s0, 0x2000
	v_add_f32_e32 v71, v72, v73
	s_cmp_lg_u32 s0, 0x20000
	s_waitcnt lgkmcnt(0)
	s_nop 1
	v_add_f32_dpp v71, v71, v71 quad_perm:[1,0,3,2] row_mask:0xf bank_mask:0xf
	s_waitcnt lgkmcnt(0)
	s_nop 1
	v_add_f32_dpp v71, v71, v71 quad_perm:[2,3,0,1] row_mask:0xf bank_mask:0xf
	s_waitcnt lgkmcnt(0)
	s_nop 1
	v_add_f32_dpp v71, v71, v71 row_half_mirror row_mask:0xf bank_mask:0xf
	s_waitcnt lgkmcnt(0)
	s_nop 1
	v_add_f32_dpp v71, v71, v71 row_mirror row_mask:0xf bank_mask:0xf
	s_waitcnt lgkmcnt(0)
	v_mov_b32_e32 v72, v71
	s_nop 1
	v_permlane16_swap_b32_e32 v71, v72
	v_add_f32_e32 v71, v71, v72
	s_waitcnt lgkmcnt(0)
	v_mov_b32_e32 v72, v71
	s_nop 1
	v_permlane32_swap_b32_e32 v71, v72
	v_add_f32_e32 v71, v71, v72
	v_cndmask_b32_e32 v70, v70, v71, vcc
	s_cbranch_scc1 .LBB0_816
	s_and_saveexec_b64 s[0:1], s[2:3]
	s_cbranch_execz .LBB0_814
	v_lshl_add_u32 v1, s31, 6, v58
	v_add_f32_e32 v0, v70, v204
	ds_write_b32 v1, v0
	s_branch .LBB0_814

.LBB0_1271:
	v_add_co_u32_e32 v8, vcc, 0xf4000000, v4
	v_add_co_u32_e64 v10, s[0:1], s34, v4
	s_nop 0
	v_addc_co_u32_e32 v9, vcc, -1, v5, vcc
	v_addc_co_u32_e64 v11, s[0:1], -1, v5, s[0:1]
	global_load_dwordx2 v[6:7], v[4:5], off
	global_load_dwordx2 v[12:13], v[4:5], off offset:512
	global_load_dwordx2 v[14:15], v[4:5], off offset:1024
	global_load_dwordx2 v[16:17], v[4:5], off offset:1536
	global_load_dwordx2 v[18:19], v[4:5], off offset:2048
	global_load_dwordx2 v[20:21], v[4:5], off offset:2560
	global_load_dwordx2 v[34:35], v[4:5], off offset:3072
	global_load_dwordx2 v[36:37], v[4:5], off offset:3584
	global_load_dwordx2 v[42:43], v[10:11], off offset:-3584
	global_load_dwordx2 v[44:45], v[10:11], off offset:-3072
	global_load_dwordx2 v[50:51], v[10:11], off offset:-2560
	global_load_dwordx2 v[52:53], v[10:11], off offset:-2048
	global_load_dwordx2 v[70:71], v[10:11], off offset:-1536
	global_load_dwordx2 v[72:73], v[10:11], off offset:-1024
	global_load_dwordx2 v[74:75], v[10:11], off offset:-512
	global_load_dwordx2 v[76:77], v[8:9], off
	v_add_co_u32_e32 v22, vcc, 0x4000000, v4
	s_add_i32 s35, s35, s36
	s_nop 0
	v_addc_co_u32_e32 v23, vcc, 0, v5, vcc
	global_load_dwordx2 v[78:79], v[22:23], off
	global_load_dwordx2 v[80:81], v[22:23], off offset:512
	global_load_dwordx2 v[82:83], v[22:23], off offset:1024
	global_load_dwordx2 v[84:85], v[22:23], off offset:1536
	global_load_dwordx2 v[114:115], v[22:23], off offset:2048
	global_load_dwordx2 v[116:117], v[22:23], off offset:2560
	global_load_dwordx2 v[118:119], v[22:23], off offset:3072
	global_load_dwordx2 v[120:121], v[22:23], off offset:3584
	s_cmpk_lt_i32 s35, 0x4000
	v_lshl_add_u64 v[4:5], v[4:5], 0, s[30:31]
	s_waitcnt vmcnt(0)
	v_lshlrev_b32_e32 v46, 16, v6
	v_lshlrev_b32_e32 v38, 16, v12
	v_and_b32_e32 v39, 0xffff0000, v12
	v_and_b32_e32 v67, 0xffff0000, v43
	v_and_b32_e32 v69, 0xffff0000, v42
	v_lshlrev_b32_e32 v40, 16, v13
	v_and_b32_e32 v41, 0xffff0000, v13
	v_lshlrev_b32_e32 v26, 16, v16
	v_and_b32_e32 v27, 0xffff0000, v16
	v_lshlrev_b32_e32 v28, 16, v17
	v_and_b32_e32 v29, 0xffff0000, v17
	v_lshlrev_b32_e32 v16, 16, v35
	v_and_b32_e32 v17, 0xffff0000, v35
	v_lshlrev_b32_e32 v12, 16, v37
	v_and_b32_e32 v13, 0xffff0000, v37
	v_lshlrev_b32_e32 v66, 16, v43
	v_lshlrev_b32_e32 v68, 16, v42
	v_lshlrev_b32_e32 v62, 16, v45
	v_and_b32_e32 v63, 0xffff0000, v45
	v_and_b32_e32 v65, 0xffff0000, v44
	v_lshlrev_b32_e32 v58, 16, v51
	v_and_b32_e32 v59, 0xffff0000, v51
	v_lshlrev_b32_e32 v60, 16, v50
	v_and_b32_e32 v61, 0xffff0000, v50
	v_lshlrev_b32_e32 v54, 16, v53
	v_and_b32_e32 v55, 0xffff0000, v53
	v_lshlrev_b32_e32 v56, 16, v52
	v_and_b32_e32 v57, 0xffff0000, v52
	v_lshlrev_b32_e32 v50, 16, v71
	v_and_b32_e32 v51, 0xffff0000, v71
	v_lshlrev_b32_e32 v52, 16, v70
	v_and_b32_e32 v53, 0xffff0000, v70
	v_and_b32_e32 v43, 0xffff0000, v73
	v_and_b32_e32 v45, 0xffff0000, v72
	v_and_b32_e32 v35, 0xffff0000, v75
	v_and_b32_e32 v37, 0xffff0000, v74
	v_and_b32_e32 v95, 0xffff0000, v77
	v_and_b32_e32 v97, 0xffff0000, v76
	v_mov_b32_e32 v70, v69
	v_mov_b32_e32 v71, v67
	v_and_b32_e32 v47, 0xffff0000, v6
	v_lshlrev_b32_e32 v48, 16, v7
	v_and_b32_e32 v49, 0xffff0000, v7
	v_lshlrev_b32_e32 v30, 16, v14
	v_and_b32_e32 v31, 0xffff0000, v14
	v_lshlrev_b32_e32 v32, 16, v15
	v_and_b32_e32 v33, 0xffff0000, v15
	v_lshlrev_b32_e32 v14, 16, v34
	v_and_b32_e32 v15, 0xffff0000, v34
	v_lshlrev_b32_e32 v6, 16, v36
	v_and_b32_e32 v7, 0xffff0000, v36
	v_lshlrev_b32_e32 v64, 16, v44
	v_lshlrev_b32_e32 v42, 16, v73
	v_lshlrev_b32_e32 v44, 16, v72
	v_lshlrev_b32_e32 v34, 16, v75
	v_lshlrev_b32_e32 v36, 16, v74
	v_lshlrev_b32_e32 v94, 16, v77
	v_lshlrev_b32_e32 v96, 16, v76
	v_mov_b32_e32 v122, v68
	v_mov_b32_e32 v123, v66
	v_mov_b32_e32 v72, v65
	v_mov_b32_e32 v73, v63
	v_mov_b32_e32 v74, v61
	v_mov_b32_e32 v75, v59
	v_mov_b32_e32 v76, v57
	v_mov_b32_e32 v77, v55
	v_mov_b32_e32 v132, v53
	v_mov_b32_e32 v133, v51
	v_mov_b32_e32 v136, v45
	v_mov_b32_e32 v137, v43
	v_mov_b32_e32 v140, v37
	v_mov_b32_e32 v141, v35
	v_mov_b32_e32 v144, v97
	v_mov_b32_e32 v145, v95
	v_pk_mul_f32 v[146:147], v[70:71], v[70:71]
	v_mov_b32_e32 v124, v64
	v_mov_b32_e32 v125, v62
	v_mov_b32_e32 v128, v56
	v_mov_b32_e32 v129, v54
	v_mov_b32_e32 v130, v52
	v_mov_b32_e32 v131, v50
	v_mov_b32_e32 v134, v44
	v_mov_b32_e32 v135, v42
	v_mov_b32_e32 v138, v36
	v_mov_b32_e32 v139, v34
	v_mov_b32_e32 v142, v96
	v_mov_b32_e32 v143, v94
	v_lshlrev_b32_e32 v102, 16, v78
	v_and_b32_e32 v103, 0xffff0000, v78
	v_lshlrev_b32_e32 v104, 16, v79
	v_and_b32_e32 v105, 0xffff0000, v79
	v_lshlrev_b32_e32 v98, 16, v80
	v_and_b32_e32 v99, 0xffff0000, v80
	v_lshlrev_b32_e32 v100, 16, v81
	v_and_b32_e32 v101, 0xffff0000, v81
	v_pk_mul_f32 v[148:149], v[72:73], v[72:73]
	v_lshlrev_b32_e32 v90, 16, v82
	v_and_b32_e32 v91, 0xffff0000, v82
	v_lshlrev_b32_e32 v92, 16, v83
	v_and_b32_e32 v93, 0xffff0000, v83
	v_pk_mul_f32 v[150:151], v[74:75], v[74:75]
	v_lshlrev_b32_e32 v86, 16, v84
	v_and_b32_e32 v87, 0xffff0000, v84
	v_lshlrev_b32_e32 v88, 16, v85
	v_and_b32_e32 v89, 0xffff0000, v85
	v_pk_mul_f32 v[152:153], v[76:77], v[76:77]
	v_lshlrev_b32_e32 v82, 16, v114
	v_and_b32_e32 v83, 0xffff0000, v114
	v_lshlrev_b32_e32 v84, 16, v115
	v_and_b32_e32 v85, 0xffff0000, v115
	v_pk_mul_f32 v[114:115], v[132:133], v[132:133]
	v_lshlrev_b32_e32 v78, 16, v116
	v_and_b32_e32 v79, 0xffff0000, v116
	v_lshlrev_b32_e32 v80, 16, v117
	v_and_b32_e32 v81, 0xffff0000, v117
	v_pk_mul_f32 v[116:117], v[136:137], v[136:137]
	v_lshlrev_b32_e32 v74, 16, v118
	v_and_b32_e32 v75, 0xffff0000, v118
	v_lshlrev_b32_e32 v76, 16, v119
	v_and_b32_e32 v77, 0xffff0000, v119
	v_pk_mul_f32 v[118:119], v[140:141], v[140:141]
	v_lshlrev_b32_e32 v70, 16, v120
	v_and_b32_e32 v71, 0xffff0000, v120
	v_lshlrev_b32_e32 v72, 16, v121
	v_and_b32_e32 v73, 0xffff0000, v121
	v_pk_mul_f32 v[120:121], v[144:145], v[144:145]
	v_pk_fma_f32 v[122:123], v[122:123], v[122:123], v[146:147]
	v_mov_b32_e32 v126, v60
	v_mov_b32_e32 v127, v58
	v_pk_fma_f32 v[124:125], v[124:125], v[124:125], v[148:149]
	v_pk_fma_f32 v[128:129], v[128:129], v[128:129], v[152:153]
	v_pk_fma_f32 v[114:115], v[130:131], v[130:131], v[114:115]
	v_pk_fma_f32 v[116:117], v[134:135], v[134:135], v[116:117]
	v_pk_fma_f32 v[118:119], v[138:139], v[138:139], v[118:119]
	v_pk_fma_f32 v[120:121], v[142:143], v[142:143], v[120:121]
	v_add_f32_e32 v122, v122, v123
	v_pk_fma_f32 v[126:127], v[126:127], v[126:127], v[150:151]
	v_add_f32_e32 v123, v124, v125
	v_add_f32_e32 v125, v128, v129
	v_add_f32_e32 v114, v114, v115
	v_add_f32_e32 v115, v116, v117
	v_add_f32_e32 v116, v118, v119
	v_add_f32_e32 v117, v120, v121
	v_add_f32_e32 v124, v126, v127
	s_waitcnt lgkmcnt(6)
	s_nop 1
	v_add_f32_dpp v118, v122, v122 quad_perm:[1,0,3,2] row_mask:0xf bank_mask:0xf
	s_waitcnt lgkmcnt(6)
	s_nop 1
	v_add_f32_dpp v119, v123, v123 quad_perm:[1,0,3,2] row_mask:0xf bank_mask:0xf
	s_waitcnt lgkmcnt(5)
	s_nop 1
	v_add_f32_dpp v121, v125, v125 quad_perm:[1,0,3,2] row_mask:0xf bank_mask:0xf
	s_waitcnt lgkmcnt(4)
	s_nop 1
	v_add_f32_dpp v114, v114, v114 quad_perm:[1,0,3,2] row_mask:0xf bank_mask:0xf
	s_waitcnt lgkmcnt(3)
	s_nop 1
	v_add_f32_dpp v117, v117, v117 quad_perm:[1,0,3,2] row_mask:0xf bank_mask:0xf
	s_waitcnt lgkmcnt(3)
	s_nop 1
	v_add_f32_dpp v120, v124, v124 quad_perm:[1,0,3,2] row_mask:0xf bank_mask:0xf
	s_waitcnt lgkmcnt(2)
	s_nop 1
	v_add_f32_dpp v116, v116, v116 quad_perm:[1,0,3,2] row_mask:0xf bank_mask:0xf
	s_waitcnt lgkmcnt(7)
	s_nop 1
	v_add_f32_dpp v115, v115, v115 quad_perm:[1,0,3,2] row_mask:0xf bank_mask:0xf
	s_waitcnt lgkmcnt(6)
	s_nop 1
	v_add_f32_dpp v118, v118, v118 quad_perm:[2,3,0,1] row_mask:0xf bank_mask:0xf
	s_waitcnt lgkmcnt(6)
	s_nop 1
	v_add_f32_dpp v119, v119, v119 quad_perm:[2,3,0,1] row_mask:0xf bank_mask:0xf
	s_waitcnt lgkmcnt(5)
	s_nop 1
	v_add_f32_dpp v121, v121, v121 quad_perm:[2,3,0,1] row_mask:0xf bank_mask:0xf
	s_waitcnt lgkmcnt(4)
	s_nop 1
	v_add_f32_dpp v114, v114, v114 quad_perm:[2,3,0,1] row_mask:0xf bank_mask:0xf
	s_waitcnt lgkmcnt(3)
	s_nop 1
	v_add_f32_dpp v117, v117, v117 quad_perm:[2,3,0,1] row_mask:0xf bank_mask:0xf
	s_waitcnt lgkmcnt(3)
	s_nop 1
	v_add_f32_dpp v120, v120, v120 quad_perm:[2,3,0,1] row_mask:0xf bank_mask:0xf
	s_waitcnt lgkmcnt(2)
	s_nop 1
	v_add_f32_dpp v116, v116, v116 quad_perm:[2,3,0,1] row_mask:0xf bank_mask:0xf
	s_waitcnt lgkmcnt(7)
	s_nop 1
	v_add_f32_dpp v115, v115, v115 quad_perm:[2,3,0,1] row_mask:0xf bank_mask:0xf
	s_waitcnt lgkmcnt(6)
	s_nop 1
	v_add_f32_dpp v118, v118, v118 row_half_mirror row_mask:0xf bank_mask:0xf
	s_waitcnt lgkmcnt(6)
	s_nop 1
	v_add_f32_dpp v119, v119, v119 row_half_mirror row_mask:0xf bank_mask:0xf
	s_waitcnt lgkmcnt(5)
	s_nop 1
	v_add_f32_dpp v121, v121, v121 row_half_mirror row_mask:0xf bank_mask:0xf
	s_waitcnt lgkmcnt(4)
	s_nop 1
	v_add_f32_dpp v114, v114, v114 row_half_mirror row_mask:0xf bank_mask:0xf
	s_waitcnt lgkmcnt(3)
	s_nop 1
	v_add_f32_dpp v117, v117, v117 row_half_mirror row_mask:0xf bank_mask:0xf
	s_waitcnt lgkmcnt(3)
	s_nop 1
	v_add_f32_dpp v120, v120, v120 row_half_mirror row_mask:0xf bank_mask:0xf
	s_waitcnt lgkmcnt(2)
	s_nop 1
	v_add_f32_dpp v116, v116, v116 row_half_mirror row_mask:0xf bank_mask:0xf
	s_waitcnt lgkmcnt(7)
	s_nop 1
	v_add_f32_dpp v115, v115, v115 row_half_mirror row_mask:0xf bank_mask:0xf
	s_waitcnt lgkmcnt(6)
	s_nop 1
	v_add_f32_dpp v118, v118, v118 row_mirror row_mask:0xf bank_mask:0xf
	s_waitcnt lgkmcnt(6)
	s_nop 1
	v_add_f32_dpp v119, v119, v119 row_mirror row_mask:0xf bank_mask:0xf
	s_waitcnt lgkmcnt(5)
	s_nop 1
	v_add_f32_dpp v121, v121, v121 row_mirror row_mask:0xf bank_mask:0xf
	s_waitcnt lgkmcnt(4)
	s_nop 1
	v_add_f32_dpp v114, v114, v114 row_mirror row_mask:0xf bank_mask:0xf
	s_waitcnt lgkmcnt(3)
	s_nop 1
	v_add_f32_dpp v117, v117, v117 row_mirror row_mask:0xf bank_mask:0xf
	s_waitcnt lgkmcnt(3)
	s_nop 1
	v_add_f32_dpp v120, v120, v120 row_mirror row_mask:0xf bank_mask:0xf
	s_waitcnt lgkmcnt(2)
	s_nop 1
	v_add_f32_dpp v116, v116, v116 row_mirror row_mask:0xf bank_mask:0xf
	s_waitcnt lgkmcnt(7)
	s_nop 1
	v_add_f32_dpp v115, v115, v115 row_mirror row_mask:0xf bank_mask:0xf
	s_waitcnt lgkmcnt(6)
	v_mov_b32_e32 v122, v118
	s_nop 1
	v_permlane16_swap_b32_e32 v118, v122
	v_add_f32_e32 v118, v118, v122
	s_waitcnt lgkmcnt(6)
	v_mov_b32_e32 v123, v119
	s_nop 1
	v_permlane16_swap_b32_e32 v119, v123
	v_add_f32_e32 v119, v119, v123
	s_waitcnt lgkmcnt(5)
	v_mov_b32_e32 v125, v121
	s_nop 1
	v_permlane16_swap_b32_e32 v121, v125
	v_add_f32_e32 v121, v121, v125
	s_waitcnt lgkmcnt(4)
	v_mov_b32_e32 v126, v114
	s_nop 1
	v_permlane16_swap_b32_e32 v114, v126
	v_add_f32_e32 v114, v114, v126
	s_waitcnt lgkmcnt(3)
	v_mov_b32_e32 v129, v117
	s_nop 1
	v_permlane16_swap_b32_e32 v117, v129
	v_add_f32_e32 v117, v117, v129
	s_waitcnt lgkmcnt(3)
	v_mov_b32_e32 v124, v120
	s_nop 1
	v_permlane16_swap_b32_e32 v120, v124
	v_add_f32_e32 v120, v120, v124
	s_waitcnt lgkmcnt(2)
	v_mov_b32_e32 v128, v116
	s_nop 1
	v_permlane16_swap_b32_e32 v116, v128
	v_add_f32_e32 v116, v116, v128
	s_waitcnt lgkmcnt(7)
	v_mov_b32_e32 v127, v115
	s_nop 1
	v_permlane16_swap_b32_e32 v115, v127
	v_add_f32_e32 v115, v115, v127
	s_waitcnt lgkmcnt(6)
	v_mov_b32_e32 v122, v118
	s_nop 1
	v_permlane32_swap_b32_e32 v118, v122
	v_add_f32_e32 v118, v118, v122
	s_waitcnt lgkmcnt(6)
	v_mov_b32_e32 v123, v119
	s_nop 1
	v_permlane32_swap_b32_e32 v119, v123
	v_add_f32_e32 v119, v119, v123
	s_waitcnt lgkmcnt(5)
	v_mov_b32_e32 v125, v121
	s_nop 1
	v_permlane32_swap_b32_e32 v121, v125
	v_add_f32_e32 v121, v121, v125
	s_waitcnt lgkmcnt(4)
	v_mov_b32_e32 v126, v114
	s_nop 1
	v_permlane32_swap_b32_e32 v114, v126
	v_add_f32_e32 v114, v114, v126
	s_waitcnt lgkmcnt(3)
	v_mov_b32_e32 v129, v117
	s_nop 1
	v_permlane32_swap_b32_e32 v117, v129
	v_add_f32_e32 v117, v117, v129
	v_fmamk_f32 v118, v118, 0x3b800000, v112
	s_waitcnt lgkmcnt(2)
	v_mov_b32_e32 v124, v120
	s_nop 1
	v_permlane32_swap_b32_e32 v120, v124
	v_add_f32_e32 v120, v120, v124
	s_waitcnt lgkmcnt(1)
	v_mov_b32_e32 v128, v116
	s_nop 1
	v_permlane32_swap_b32_e32 v116, v128
	v_add_f32_e32 v116, v116, v128
	v_fmamk_f32 v119, v119, 0x3b800000, v112
	v_fmamk_f32 v121, v121, 0x3b800000, v112
	v_fmamk_f32 v114, v114, 0x3b800000, v112
	v_fmamk_f32 v117, v117, 0x3b800000, v112
	v_mul_f32_e32 v122, 0x4f800000, v118
	v_cmp_gt_f32_e32 vcc, s33, v118
	v_fmamk_f32 v120, v120, 0x3b800000, v112
	v_fmamk_f32 v116, v116, 0x3b800000, v112
	v_mul_f32_e32 v123, 0x4f800000, v119
	v_cmp_gt_f32_e64 s[0:1], s33, v119
	v_mul_f32_e32 v125, 0x4f800000, v121
	v_cmp_gt_f32_e64 s[4:5], s33, v121
	v_mul_f32_e32 v126, 0x4f800000, v114
	v_cmp_gt_f32_e64 s[6:7], s33, v114
	v_mul_f32_e32 v129, 0x4f800000, v117
	v_cndmask_b32_e32 v118, v118, v122, vcc
	v_cmp_gt_f32_e64 s[12:13], s33, v117
	v_mul_f32_e32 v124, 0x4f800000, v120
	v_cmp_gt_f32_e64 s[2:3], s33, v120
	v_mul_f32_e32 v128, 0x4f800000, v116
	v_cmp_gt_f32_e64 s[10:11], s33, v116
	v_cndmask_b32_e64 v119, v119, v123, s[0:1]
	v_cndmask_b32_e64 v121, v121, v125, s[4:5]
	v_cndmask_b32_e64 v114, v114, v126, s[6:7]
	v_cndmask_b32_e64 v117, v117, v129, s[12:13]
	v_sqrt_f32_e32 v122, v118
	v_cndmask_b32_e64 v120, v120, v124, s[2:3]
	v_cndmask_b32_e64 v116, v116, v128, s[10:11]
	v_sqrt_f32_e32 v123, v119
	v_sqrt_f32_e32 v125, v121
	v_sqrt_f32_e32 v126, v114
	v_sqrt_f32_e32 v129, v117
	s_waitcnt lgkmcnt(0)
	v_mov_b32_e32 v127, v115
	s_nop 1
	v_permlane32_swap_b32_e32 v115, v127
	v_add_f32_e32 v115, v115, v127
	v_sqrt_f32_e32 v124, v120
	v_sqrt_f32_e32 v128, v116
	v_fmamk_f32 v115, v115, 0x3b800000, v112
	v_mul_f32_e32 v127, 0x4f800000, v115
	v_cmp_gt_f32_e64 s[8:9], s33, v115
	v_add_u32_e32 v130, -1, v122
	v_add_u32_e32 v131, 1, v122
	v_cndmask_b32_e64 v115, v115, v127, s[8:9]
	v_add_u32_e32 v132, -1, v123
	v_add_u32_e32 v136, -1, v125
	v_add_u32_e32 v138, -1, v126
	v_add_u32_e32 v144, -1, v129
	v_fma_f32 v146, -v130, v122, v118
	v_sqrt_f32_e32 v127, v115
	v_add_u32_e32 v133, 1, v123
	v_add_u32_e32 v134, -1, v124
	v_add_u32_e32 v137, 1, v125
	v_add_u32_e32 v139, 1, v126
	v_add_u32_e32 v142, -1, v128
	v_add_u32_e32 v145, 1, v129
	v_fma_f32 v147, -v131, v122, v118
	v_fma_f32 v148, -v132, v123, v119
	v_fma_f32 v152, -v136, v125, v121
	v_fma_f32 v154, -v138, v126, v114
	v_fma_f32 v160, -v144, v129, v117
	v_cmp_ge_f32_e64 s[14:15], 0, v146
	v_add_u32_e32 v135, 1, v124
	v_add_u32_e32 v143, 1, v128
	v_fma_f32 v149, -v133, v123, v119
	v_fma_f32 v150, -v134, v124, v120
	v_fma_f32 v153, -v137, v125, v121
	v_fma_f32 v155, -v139, v126, v114
	v_fma_f32 v158, -v142, v128, v116
	v_fma_f32 v161, -v145, v129, v117
	v_cndmask_b32_e64 v122, v122, v130, s[14:15]
	v_cmp_lt_f32_e64 s[14:15], 0, v147
	v_cmp_ge_f32_e64 s[16:17], 0, v148
	v_cmp_ge_f32_e64 s[20:21], 0, v152
	v_cmp_ge_f32_e64 s[22:23], 0, v154
	v_cmp_ge_f32_e64 s[28:29], 0, v160
	v_fma_f32 v151, -v135, v124, v120
	v_fma_f32 v159, -v143, v128, v116
	v_cndmask_b32_e64 v123, v123, v132, s[16:17]
	v_cmp_lt_f32_e64 s[16:17], 0, v149
	v_cmp_ge_f32_e64 s[18:19], 0, v150
	v_cndmask_b32_e64 v125, v125, v136, s[20:21]
	v_cmp_lt_f32_e64 s[20:21], 0, v153
	v_cndmask_b32_e64 v126, v126, v138, s[22:23]
	v_cmp_lt_f32_e64 s[22:23], 0, v155
	v_cmp_ge_f32_e64 s[26:27], 0, v158
	v_cndmask_b32_e64 v129, v129, v144, s[28:29]
	v_cndmask_b32_e64 v122, v122, v131, s[14:15]
	v_cmp_lt_f32_e64 s[14:15], 0, v161
	v_cndmask_b32_e64 v124, v124, v134, s[18:19]
	v_cmp_lt_f32_e64 s[18:19], 0, v151
	v_cndmask_b32_e64 v128, v128, v142, s[26:27]
	v_cmp_lt_f32_e64 s[26:27], 0, v159
	v_cndmask_b32_e64 v123, v123, v133, s[16:17]
	v_cndmask_b32_e64 v125, v125, v137, s[20:21]
	v_cndmask_b32_e64 v126, v126, v139, s[22:23]
	v_cndmask_b32_e64 v129, v129, v145, s[14:15]
	v_mul_f32_e32 v130, 0x37800000, v122
	v_add_u32_e32 v140, -1, v127
	v_cndmask_b32_e64 v124, v124, v135, s[18:19]
	v_cndmask_b32_e64 v128, v128, v143, s[26:27]
	v_mul_f32_e32 v131, 0x37800000, v123
	v_mul_f32_e32 v133, 0x37800000, v125
	v_mul_f32_e32 v134, 0x37800000, v126
	v_mul_f32_e32 v137, 0x37800000, v129
	v_cndmask_b32_e32 v122, v122, v130, vcc
	v_cmp_class_f32_e32 vcc, v118, v113
	v_add_u32_e32 v141, 1, v127
	v_fma_f32 v156, -v140, v127, v115
	v_mul_f32_e32 v132, 0x37800000, v124
	v_mul_f32_e32 v136, 0x37800000, v128
	v_cndmask_b32_e64 v123, v123, v131, s[0:1]
	v_cmp_class_f32_e64 s[0:1], v119, v113
	v_cndmask_b32_e64 v125, v125, v133, s[4:5]
	v_cmp_class_f32_e64 s[4:5], v121, v113
	v_cndmask_b32_e64 v126, v126, v134, s[6:7]
	v_cmp_class_f32_e64 s[6:7], v114, v113
	v_cndmask_b32_e64 v129, v129, v137, s[12:13]
	v_cndmask_b32_e32 v118, v122, v118, vcc
	v_cmp_class_f32_e32 vcc, v117, v113
	v_fma_f32 v157, -v141, v127, v115
	v_cmp_ge_f32_e64 s[24:25], 0, v156
	v_cndmask_b32_e64 v124, v124, v132, s[2:3]
	v_cmp_class_f32_e64 s[2:3], v120, v113
	v_cndmask_b32_e64 v128, v128, v136, s[10:11]
	v_cmp_class_f32_e64 s[10:11], v116, v113
	v_cndmask_b32_e64 v119, v123, v119, s[0:1]
	v_cndmask_b32_e64 v121, v125, v121, s[4:5]
	v_cndmask_b32_e64 v122, v126, v114, s[6:7]
	v_cndmask_b32_e32 v114, v129, v117, vcc
	v_cndmask_b32_e64 v127, v127, v140, s[24:25]
	v_cmp_lt_f32_e64 s[24:25], 0, v157
	v_cndmask_b32_e64 v120, v124, v120, s[2:3]
	v_cndmask_b32_e64 v116, v128, v116, s[10:11]
	v_div_scale_f32 v117, s[0:1], v118, v118, 1.0
	v_div_scale_f32 v124, s[0:1], v119, v119, 1.0
	v_div_scale_f32 v128, s[0:1], v121, v121, 1.0
	v_div_scale_f32 v136, s[14:15], v114, v114, 1.0
	v_cndmask_b32_e64 v127, v127, v141, s[24:25]
	v_rcp_f32_e32 v138, v117
	v_rcp_f32_e32 v139, v124
	v_rcp_f32_e32 v141, v128
	v_rcp_f32_e32 v145, v136
	v_mul_f32_e32 v135, 0x37800000, v127
	v_div_scale_f32 v126, s[0:1], v120, v120, 1.0
	v_cndmask_b32_e64 v127, v127, v135, s[8:9]
	v_cmp_class_f32_e64 s[8:9], v115, v113
	v_rcp_f32_e32 v140, v126
	v_div_scale_f32 v130, s[0:1], v122, v122, 1.0
	v_cndmask_b32_e64 v115, v127, v115, s[8:9]
	v_fma_f32 v146, -v117, v138, 1.0
	v_fma_f32 v147, -v124, v139, 1.0
	v_fma_f32 v149, -v128, v141, 1.0
	v_fma_f32 v153, -v136, v145, 1.0
	v_div_scale_f32 v123, s[4:5], 1.0, v118, 1.0
	v_div_scale_f32 v125, s[6:7], 1.0, v119, 1.0
	v_div_scale_f32 v129, s[10:11], 1.0, v121, 1.0
	v_div_scale_f32 v132, s[0:1], v115, v115, 1.0
	v_div_scale_f32 v137, vcc, 1.0, v114, 1.0
	v_rcp_f32_e32 v142, v130
	v_fmac_f32_e32 v138, v146, v138
	v_fmac_f32_e32 v139, v147, v139
	v_fmac_f32_e32 v141, v149, v141
	v_fmac_f32_e32 v145, v153, v145
	v_div_scale_f32 v134, s[0:1], v116, v116, 1.0
	v_rcp_f32_e32 v143, v132
	v_mul_f32_e32 v146, v123, v138
	v_mul_f32_e32 v147, v125, v139
	v_mul_f32_e32 v149, v129, v141
	v_mul_f32_e32 v153, v137, v145
	v_rcp_f32_e32 v144, v134
	v_fma_f32 v148, -v126, v140, 1.0
	v_fma_f32 v154, -v117, v146, v123
	v_fma_f32 v155, -v124, v147, v125
	v_fma_f32 v157, -v128, v149, v129
	v_fma_f32 v161, -v136, v153, v137
	v_div_scale_f32 v127, s[8:9], 1.0, v120, 1.0
	v_fmac_f32_e32 v140, v148, v140
	v_fmac_f32_e32 v146, v154, v138
	v_fmac_f32_e32 v147, v155, v139
	v_fmac_f32_e32 v149, v157, v141
	v_fmac_f32_e32 v153, v161, v145
	v_fma_f32 v150, -v130, v142, 1.0
	v_mul_f32_e32 v148, v127, v140
	v_fma_f32 v117, -v117, v146, v123
	v_fma_f32 v123, -v124, v147, v125
	v_fma_f32 v125, -v128, v149, v129
	v_fma_f32 v129, -v136, v153, v137
	v_div_scale_f32 v131, s[12:13], 1.0, v122, 1.0
	v_fma_f32 v151, -v132, v143, 1.0
	v_fmac_f32_e32 v142, v150, v142
	v_fma_f32 v156, -v126, v148, v127
	v_div_fmas_f32 v129, v129, v145, v153
	s_mov_b64 vcc, s[4:5]
	v_div_scale_f32 v133, s[2:3], 1.0, v115, 1.0
	v_fma_f32 v152, -v134, v144, 1.0
	v_fmac_f32_e32 v143, v151, v143
	v_mul_f32_e32 v150, v131, v142
	v_fmac_f32_e32 v148, v156, v140
	v_div_fixup_f32 v114, v129, v114, 1.0
	v_div_fmas_f32 v117, v117, v138, v146
	s_mov_b64 vcc, s[6:7]
	v_div_scale_f32 v135, s[0:1], 1.0, v116, 1.0
	v_fmac_f32_e32 v144, v152, v144
	v_mul_f32_e32 v151, v133, v143
	v_fma_f32 v158, -v130, v150, v131
	v_fma_f32 v124, -v126, v148, v127
	v_pk_mul_f32 v[96:97], v[114:115], v[96:97] op_sel_hi:[0,1]
	v_pk_mul_f32 v[94:95], v[114:115], v[94:95] op_sel_hi:[0,1]
	v_div_fixup_f32 v114, v117, v118, 1.0
	v_div_fmas_f32 v117, v123, v139, v147
	s_mov_b64 vcc, s[8:9]
	v_mul_f32_e32 v152, v135, v144
	v_fma_f32 v159, -v132, v151, v133
	v_fmac_f32_e32 v150, v158, v142
	v_pk_mul_f32 v[96:97], v[0:1], v[96:97]
	v_pk_mul_f32 v[94:95], v[2:3], v[94:95]
	v_pk_mul_f32 v[68:69], v[114:115], v[68:69] op_sel_hi:[0,1]
	v_pk_mul_f32 v[66:67], v[114:115], v[66:67] op_sel_hi:[0,1]
	v_div_fixup_f32 v114, v117, v119, 1.0
	v_div_fmas_f32 v117, v124, v140, v148
	s_mov_b64 vcc, s[10:11]
	v_fma_f32 v160, -v134, v152, v135
	v_fmac_f32_e32 v151, v159, v143
	v_fma_f32 v126, -v130, v150, v131
	v_pk_mul_f32 v[46:47], v[96:97], v[46:47]
	v_pk_mul_f32 v[48:49], v[94:95], v[48:49]
	v_pk_mul_f32 v[68:69], v[0:1], v[68:69]
	v_pk_mul_f32 v[66:67], v[2:3], v[66:67]
	v_pk_mul_f32 v[64:65], v[114:115], v[64:65] op_sel_hi:[0,1]
	v_pk_mul_f32 v[62:63], v[114:115], v[62:63] op_sel_hi:[0,1]
	v_div_fixup_f32 v94, v117, v120, 1.0
	v_div_fmas_f32 v95, v125, v141, v149
	s_mov_b64 vcc, s[12:13]
	v_fmac_f32_e32 v152, v160, v144
	v_fma_f32 v127, -v132, v151, v133
	v_pk_mul_f32 v[46:47], v[46:47], v[102:103]
	v_pk_mul_f32 v[48:49], v[48:49], v[104:105]
	v_pk_mul_f32 v[38:39], v[68:69], v[38:39]
	v_pk_mul_f32 v[40:41], v[66:67], v[40:41]
	v_pk_mul_f32 v[64:65], v[0:1], v[64:65]
	v_pk_mul_f32 v[62:63], v[2:3], v[62:63]
	v_pk_mul_f32 v[60:61], v[94:95], v[60:61] op_sel_hi:[0,1]
	v_pk_mul_f32 v[58:59], v[94:95], v[58:59] op_sel_hi:[0,1]
	v_div_fixup_f32 v66, v95, v121, 1.0
	v_div_fmas_f32 v67, v126, v142, v150
	s_mov_b64 vcc, s[2:3]
	v_fma_f32 v128, -v134, v152, v135
	v_cvt_pk_bf16_f32 v46, v46, v47
	v_cvt_pk_bf16_f32 v47, v48, v49
	v_pk_mul_f32 v[38:39], v[38:39], v[98:99]
	v_pk_mul_f32 v[40:41], v[40:41], v[100:101]
	v_pk_mul_f32 v[30:31], v[64:65], v[30:31]
	v_pk_mul_f32 v[32:33], v[62:63], v[32:33]
	v_pk_mul_f32 v[48:49], v[0:1], v[60:61]
	v_pk_mul_f32 v[58:59], v[2:3], v[58:59]
	v_pk_mul_f32 v[56:57], v[66:67], v[56:57] op_sel_hi:[0,1]
	v_pk_mul_f32 v[54:55], v[66:67], v[54:55] op_sel_hi:[0,1]
	v_div_fixup_f32 v60, v67, v122, 1.0
	v_div_fmas_f32 v61, v127, v143, v151
	s_mov_b64 vcc, s[0:1]
	v_lshlrev_b32_e32 v22, 16, v18
	v_and_b32_e32 v23, 0xffff0000, v18
	v_lshlrev_b32_e32 v24, 16, v19
	v_and_b32_e32 v25, 0xffff0000, v19
	global_store_dwordx2 v[8:9], v[46:47], off
	v_cvt_pk_bf16_f32 v8, v38, v39
	v_cvt_pk_bf16_f32 v9, v40, v41
	v_pk_mul_f32 v[30:31], v[30:31], v[90:91]
	v_pk_mul_f32 v[32:33], v[32:33], v[92:93]
	v_pk_mul_f32 v[26:27], v[48:49], v[26:27]
	v_pk_mul_f32 v[28:29], v[58:59], v[28:29]
	v_pk_mul_f32 v[38:39], v[0:1], v[56:57]
	v_pk_mul_f32 v[40:41], v[2:3], v[54:55]
	v_pk_mul_f32 v[46:47], v[60:61], v[52:53] op_sel_hi:[0,1]
	v_pk_mul_f32 v[48:49], v[60:61], v[50:51] op_sel_hi:[0,1]
	v_div_fixup_f32 v50, v61, v115, 1.0
	v_div_fmas_f32 v51, v128, v144, v152
	v_lshlrev_b32_e32 v18, 16, v20
	v_and_b32_e32 v19, 0xffff0000, v20
	v_lshlrev_b32_e32 v20, 16, v21
	v_and_b32_e32 v21, 0xffff0000, v21
	global_store_dwordx2 v[10:11], v[8:9], off offset:-3584
	v_cvt_pk_bf16_f32 v8, v30, v31
	v_cvt_pk_bf16_f32 v9, v32, v33
	v_pk_mul_f32 v[26:27], v[26:27], v[86:87]
	v_pk_mul_f32 v[28:29], v[28:29], v[88:89]
	v_pk_mul_f32 v[22:23], v[38:39], v[22:23]
	v_pk_mul_f32 v[24:25], v[40:41], v[24:25]
	v_pk_mul_f32 v[30:31], v[0:1], v[46:47]
	v_pk_mul_f32 v[32:33], v[2:3], v[48:49]
	v_pk_mul_f32 v[40:41], v[50:51], v[42:43] op_sel_hi:[0,1]
	v_div_fixup_f32 v42, v51, v116, 1.0
	v_pk_mul_f32 v[38:39], v[50:51], v[44:45] op_sel_hi:[0,1]
	global_store_dwordx2 v[10:11], v[8:9], off offset:-3072
	v_cvt_pk_bf16_f32 v8, v26, v27
	v_cvt_pk_bf16_f32 v9, v28, v29
	v_pk_mul_f32 v[22:23], v[22:23], v[82:83]
	v_pk_mul_f32 v[24:25], v[24:25], v[84:85]
	v_pk_mul_f32 v[18:19], v[30:31], v[18:19]
	v_pk_mul_f32 v[20:21], v[32:33], v[20:21]
	v_pk_mul_f32 v[30:31], v[42:43], v[36:37] op_sel_hi:[0,1]
	v_pk_mul_f32 v[32:33], v[42:43], v[34:35] op_sel_hi:[0,1]
	v_pk_mul_f32 v[26:27], v[0:1], v[38:39]
	v_pk_mul_f32 v[28:29], v[2:3], v[40:41]
	global_store_dwordx2 v[10:11], v[8:9], off offset:-2560
	v_cvt_pk_bf16_f32 v8, v22, v23
	v_cvt_pk_bf16_f32 v9, v24, v25
	v_pk_mul_f32 v[22:23], v[0:1], v[30:31]
	v_pk_mul_f32 v[24:25], v[2:3], v[32:33]
	v_pk_mul_f32 v[18:19], v[18:19], v[78:79]
	v_pk_mul_f32 v[20:21], v[20:21], v[80:81]
	v_pk_mul_f32 v[14:15], v[26:27], v[14:15]
	v_pk_mul_f32 v[16:17], v[28:29], v[16:17]
	v_pk_mul_f32 v[6:7], v[22:23], v[6:7]
	v_pk_mul_f32 v[12:13], v[24:25], v[12:13]
	global_store_dwordx2 v[10:11], v[8:9], off offset:-2048
	v_cvt_pk_bf16_f32 v8, v18, v19
	v_cvt_pk_bf16_f32 v9, v20, v21
	v_pk_mul_f32 v[14:15], v[14:15], v[74:75]
	v_pk_mul_f32 v[16:17], v[16:17], v[76:77]
	v_pk_mul_f32 v[6:7], v[6:7], v[70:71]
	v_pk_mul_f32 v[12:13], v[12:13], v[72:73]
	global_store_dwordx2 v[10:11], v[8:9], off offset:-1536
	v_cvt_pk_bf16_f32 v8, v14, v15
	v_cvt_pk_bf16_f32 v9, v16, v17
	v_cvt_pk_bf16_f32 v6, v6, v7
	v_cvt_pk_bf16_f32 v7, v12, v13
	global_store_dwordx2 v[10:11], v[8:9], off offset:-1024
	global_store_dwordx2 v[10:11], v[6:7], off offset:-512
	s_cbranch_scc1 .LBB0_1271

.LBB0_1408:
	global_load_dwordx4 v[34:37], v[22:23], off offset:-4096
	global_load_dwordx4 v[8:11], v[22:23], off offset:-3072
	global_load_dwordx4 v[38:41], v[22:23], off offset:-2048
	global_load_dwordx4 v[4:7], v[22:23], off
	global_load_dwordx4 v[42:45], v[22:23], off offset:-1024
	global_load_dwordx4 v[46:49], v[22:23], off offset:1024
	global_load_dwordx4 v[0:3], v[22:23], off offset:3072
	global_load_dwordx4 v[50:53], v[22:23], off offset:2048
	global_load_dwordx4 v[54:57], v[12:13], off
	s_add_i32 s7, s7, s74
	v_lshl_add_u64 v[22:23], v[22:23], 0, s[2:3]
	s_cmpk_lt_i32 s7, 0x4000
	s_waitcnt vmcnt(0)
	v_mov_b32_e32 v60, v35
	v_mov_b32_e32 v61, v9
	v_mov_b32_e32 v64, v37
	v_mov_b32_e32 v65, v11
	v_mov_b32_e32 v58, v34
	v_mov_b32_e32 v59, v8
	v_mov_b32_e32 v62, v36
	v_mov_b32_e32 v63, v10
	v_pk_mul_f32 v[66:67], v[40:41], v[40:41]
	v_pk_mul_f32 v[68:69], v[38:39], v[38:39]
	v_pk_mul_f32 v[60:61], v[60:61], v[60:61]
	v_pk_mul_f32 v[64:65], v[64:65], v[64:65]
	v_pk_mov_b32 v[82:83], v[68:69], v[66:67] op_sel:[1,0]
	v_mov_b32_e32 v69, v67
	v_pk_fma_f32 v[58:59], v[58:59], v[58:59], v[60:61]
	v_pk_fma_f32 v[60:61], v[62:63], v[62:63], v[64:65]
	v_mul_f32_e32 v70, v43, v43
	v_mul_f32_e32 v72, v45, v45
	v_pk_add_f32 v[62:63], v[82:83], v[68:69]
	v_pk_add_f32 v[58:59], v[58:59], v[60:61]
	v_mul_f32_e32 v81, v4, v4
	v_mul_f32_e32 v84, v5, v5
	v_mul_f32_e32 v85, v6, v6
	v_mul_f32_e32 v86, v7, v7
	v_pk_fma_f32 v[66:67], v[42:43], v[42:43], v[70:71] op_sel_hi:[1,1,0]
	v_pk_fma_f32 v[70:71], v[44:45], v[44:45], v[72:73] op_sel_hi:[1,1,0]
	v_pk_add_f32 v[60:61], v[62:63], v[62:63] op_sel:[0,1] op_sel_hi:[1,0]
	v_pk_add_f32 v[58:59], v[58:59], v[58:59] op_sel:[0,1] op_sel_hi:[1,0]
	v_pk_mul_f32 v[74:75], v[48:49], v[48:49]
	v_pk_mul_f32 v[76:77], v[46:47], v[46:47]
	v_mov_b32_e32 v67, v85
	v_mov_b32_e32 v71, v86
	v_mov_b32_e32 v61, v84
	v_mov_b32_e32 v59, v81
	v_pk_mov_b32 v[72:73], v[76:77], v[74:75] op_sel:[1,0]
	v_mov_b32_e32 v77, v75
	v_pk_add_f32 v[62:63], v[66:67], v[70:71]
	v_pk_add_f32 v[58:59], v[58:59], v[60:61]
	v_mul_f32_e32 v78, v51, v51
	v_mul_f32_e32 v80, v53, v53
	v_pk_add_f32 v[64:65], v[72:73], v[76:77]
	v_pk_add_f32 v[58:59], v[58:59], v[62:63]
	v_mul_f32_e32 v87, v0, v0
	v_mul_f32_e32 v88, v1, v1
	v_mul_f32_e32 v89, v2, v2
	v_mul_f32_e32 v90, v3, v3
	v_pk_fma_f32 v[74:75], v[50:51], v[50:51], v[78:79] op_sel_hi:[1,1,0]
	v_pk_fma_f32 v[78:79], v[52:53], v[52:53], v[80:81] op_sel_hi:[1,1,0]
	v_pk_add_f32 v[64:65], v[64:65], v[64:65] op_sel:[0,1] op_sel_hi:[1,0]
	v_pk_add_f32 v[58:59], v[58:59], v[58:59] op_sel:[0,1] op_sel_hi:[1,0]
	v_mov_b32_e32 v75, v89
	v_mov_b32_e32 v79, v90
	v_mov_b32_e32 v65, v88
	v_mov_b32_e32 v59, v87
	v_pk_add_f32 v[66:67], v[74:75], v[78:79]
	v_pk_add_f32 v[58:59], v[58:59], v[64:65]
	s_nop 0
	v_pk_add_f32 v[58:59], v[58:59], v[66:67]
	s_nop 0
	v_add_f32_e32 v58, v58, v59
	s_waitcnt lgkmcnt(0)
	s_nop 1
	v_add_f32_dpp v58, v58, v58 quad_perm:[1,0,3,2] row_mask:0xf bank_mask:0xf
	s_waitcnt lgkmcnt(0)
	s_nop 1
	v_add_f32_dpp v58, v58, v58 quad_perm:[2,3,0,1] row_mask:0xf bank_mask:0xf
	s_waitcnt lgkmcnt(0)
	s_nop 1
	v_add_f32_dpp v58, v58, v58 row_half_mirror row_mask:0xf bank_mask:0xf
	s_waitcnt lgkmcnt(0)
	s_nop 1
	v_add_f32_dpp v58, v58, v58 row_mirror row_mask:0xf bank_mask:0xf
	s_waitcnt lgkmcnt(0)
	v_mov_b32_e32 v59, v58
	s_nop 1
	v_permlane16_swap_b32_e32 v58, v59
	v_add_f32_e32 v58, v58, v59
	s_waitcnt lgkmcnt(0)
	v_mov_b32_e32 v59, v58
	s_nop 1
	v_permlane32_swap_b32_e32 v58, v59
	v_add_f32_e32 v58, v58, v59
	v_fmamk_f32 v58, v58, 0x3a000000, v32
	v_mul_f32_e32 v59, 0x4f800000, v58
	v_cmp_gt_f32_e32 vcc, s6, v58
	s_nop 1
	v_cndmask_b32_e32 v58, v58, v59, vcc
	v_sqrt_f32_e32 v59, v58
	s_nop 0
	v_add_u32_e32 v60, -1, v59
	v_add_u32_e32 v61, 1, v59
	v_fma_f32 v62, -v60, v59, v58
	v_fma_f32 v63, -v61, v59, v58
	v_cmp_ge_f32_e64 s[0:1], 0, v62
	s_nop 1
	v_cndmask_b32_e64 v59, v59, v60, s[0:1]
	v_cmp_lt_f32_e64 s[0:1], 0, v63
	s_nop 1
	v_cndmask_b32_e64 v59, v59, v61, s[0:1]
	v_mul_f32_e32 v60, 0x37800000, v59
	v_cndmask_b32_e32 v59, v59, v60, vcc
	v_cmp_class_f32_e32 vcc, v58, v33
	s_nop 1
	v_cndmask_b32_e32 v58, v59, v58, vcc
	v_div_scale_f32 v59, s[0:1], v58, v58, 1.0
	v_rcp_f32_e32 v61, v59
	v_div_scale_f32 v60, vcc, 1.0, v58, 1.0
	v_fma_f32 v62, -v59, v61, 1.0
	v_fmac_f32_e32 v61, v62, v61
	v_mul_f32_e32 v62, v60, v61
	v_fma_f32 v63, -v59, v62, v60
	v_fmac_f32_e32 v62, v63, v61
	v_fma_f32 v59, -v59, v62, v60
	v_div_fmas_f32 v59, v59, v61, v62
	v_div_fixup_f32 v58, v59, v58, 1.0
	v_pk_mul_f32 v[34:35], v[34:35], v[58:59] op_sel_hi:[1,0]
	v_pk_mul_f32 v[36:37], v[36:37], v[58:59] op_sel_hi:[1,0]
	v_pk_mul_f32 v[34:35], v[54:55], v[34:35]
	v_pk_mul_f32 v[36:37], v[56:57], v[36:37]
	v_cvt_pk_bf16_f32 v34, v34, v35
	v_cvt_pk_bf16_f32 v35, v36, v37
	global_store_dwordx2 v[24:25], v[34:35], off
	v_pk_mul_f32 v[8:9], v[8:9], v[58:59] op_sel_hi:[1,0]
	v_pk_mul_f32 v[10:11], v[10:11], v[58:59] op_sel_hi:[1,0]
	v_pk_mul_f32 v[4:5], v[4:5], v[58:59] op_sel_hi:[1,0]
	v_pk_mul_f32 v[6:7], v[6:7], v[58:59] op_sel_hi:[1,0]
	v_pk_mul_f32 v[0:1], v[0:1], v[58:59] op_sel_hi:[1,0]
	v_pk_mul_f32 v[2:3], v[2:3], v[58:59] op_sel_hi:[1,0]
	v_pk_mul_f32 v[10:11], v[134:135], v[10:11]
	v_pk_mul_f32 v[8:9], v[132:133], v[8:9]
	v_pk_mul_f32 v[34:35], v[38:39], v[58:59] op_sel_hi:[1,0]
	v_cvt_pk_bf16_f32 v8, v8, v9
	v_cvt_pk_bf16_f32 v9, v10, v11
	global_store_dwordx2 v[24:25], v[8:9], off offset:512
	v_pk_mul_f32 v[36:37], v[40:41], v[58:59] op_sel_hi:[1,0]
	v_pk_mul_f32 v[8:9], v[136:137], v[34:35]
	v_pk_mul_f32 v[10:11], v[138:139], v[36:37]
	v_cvt_pk_bf16_f32 v8, v8, v9
	v_cvt_pk_bf16_f32 v9, v10, v11
	global_store_dwordx2 v[24:25], v[8:9], off offset:1024
	v_pk_mul_f32 v[34:35], v[42:43], v[58:59] op_sel_hi:[1,0]
	v_pk_mul_f32 v[36:37], v[44:45], v[58:59] op_sel_hi:[1,0]
	v_pk_mul_f32 v[8:9], v[140:141], v[34:35]
	v_pk_mul_f32 v[10:11], v[142:143], v[36:37]
	v_cvt_pk_bf16_f32 v8, v8, v9
	v_cvt_pk_bf16_f32 v9, v10, v11
	global_store_dwordx2 v[24:25], v[8:9], off offset:1536
	v_pk_mul_f32 v[6:7], v[146:147], v[6:7]
	v_pk_mul_f32 v[4:5], v[144:145], v[4:5]
	v_pk_mul_f32 v[8:9], v[46:47], v[58:59] op_sel_hi:[1,0]
	v_cvt_pk_bf16_f32 v4, v4, v5
	v_cvt_pk_bf16_f32 v5, v6, v7
	global_store_dwordx2 v[24:25], v[4:5], off offset:2048
	v_pk_mul_f32 v[10:11], v[48:49], v[58:59] op_sel_hi:[1,0]
	v_pk_mul_f32 v[4:5], v[148:149], v[8:9]
	v_pk_mul_f32 v[6:7], v[150:151], v[10:11]
	v_cvt_pk_bf16_f32 v4, v4, v5
	v_cvt_pk_bf16_f32 v5, v6, v7
	global_store_dwordx2 v[24:25], v[4:5], off offset:2560
	v_pk_mul_f32 v[8:9], v[50:51], v[58:59] op_sel_hi:[1,0]
	v_pk_mul_f32 v[10:11], v[52:53], v[58:59] op_sel_hi:[1,0]
	v_pk_mul_f32 v[4:5], v[8:9], v[152:153]
	v_pk_mul_f32 v[6:7], v[10:11], v[154:155]
	v_cvt_pk_bf16_f32 v4, v4, v5
	v_cvt_pk_bf16_f32 v5, v6, v7
	global_store_dwordx2 v[24:25], v[4:5], off offset:3072
	v_pk_mul_f32 v[2:3], v[2:3], v[158:159]
	v_pk_mul_f32 v[0:1], v[0:1], v[156:157]
	s_nop 0
	v_cvt_pk_bf16_f32 v0, v0, v1
	v_cvt_pk_bf16_f32 v1, v2, v3
	global_store_dwordx2 v[24:25], v[0:1], off offset:3584
	v_lshl_add_u64 v[24:25], v[24:25], 0, s[4:5]
	s_cbranch_scc1 .LBB0_1408

.LBB0_1762:
	global_load_dwordx4 v[32:35], v[22:23], off offset:-4096
	global_load_dwordx4 v[8:11], v[22:23], off offset:-3072
	global_load_dwordx4 v[36:39], v[22:23], off offset:-2048
	global_load_dwordx4 v[4:7], v[22:23], off
	global_load_dwordx4 v[40:43], v[22:23], off offset:-1024
	global_load_dwordx4 v[44:47], v[22:23], off offset:1024
	global_load_dwordx4 v[0:3], v[22:23], off offset:3072
	global_load_dwordx4 v[48:51], v[22:23], off offset:2048
	global_load_dwordx4 v[52:55], v[12:13], off
	s_add_i32 s6, s6, s74
	s_cmpk_lt_i32 s6, 0x4000
	s_waitcnt vmcnt(0)
	v_mov_b32_e32 v58, v33
	v_mov_b32_e32 v59, v9
	v_mov_b32_e32 v62, v35
	v_mov_b32_e32 v63, v11
	v_mov_b32_e32 v56, v32
	v_mov_b32_e32 v57, v8
	v_mov_b32_e32 v60, v34
	v_mov_b32_e32 v61, v10
	v_pk_mul_f32 v[64:65], v[38:39], v[38:39]
	v_pk_mul_f32 v[66:67], v[36:37], v[36:37]
	v_pk_mul_f32 v[58:59], v[58:59], v[58:59]
	v_pk_mul_f32 v[62:63], v[62:63], v[62:63]
	v_pk_mov_b32 v[80:81], v[66:67], v[64:65] op_sel:[1,0]
	v_mov_b32_e32 v67, v65
	v_pk_fma_f32 v[56:57], v[56:57], v[56:57], v[58:59]
	v_pk_fma_f32 v[58:59], v[60:61], v[60:61], v[62:63]
	v_mul_f32_e32 v68, v41, v41
	v_mul_f32_e32 v70, v43, v43
	v_pk_add_f32 v[60:61], v[80:81], v[66:67]
	v_pk_add_f32 v[56:57], v[56:57], v[58:59]
	v_mul_f32_e32 v79, v4, v4
	v_mul_f32_e32 v82, v5, v5
	v_mul_f32_e32 v83, v6, v6
	v_mul_f32_e32 v84, v7, v7
	v_pk_fma_f32 v[64:65], v[40:41], v[40:41], v[68:69] op_sel_hi:[1,1,0]
	v_pk_fma_f32 v[68:69], v[42:43], v[42:43], v[70:71] op_sel_hi:[1,1,0]
	v_pk_add_f32 v[58:59], v[60:61], v[60:61] op_sel:[0,1] op_sel_hi:[1,0]
	v_pk_add_f32 v[56:57], v[56:57], v[56:57] op_sel:[0,1] op_sel_hi:[1,0]
	v_pk_mul_f32 v[72:73], v[46:47], v[46:47]
	v_pk_mul_f32 v[74:75], v[44:45], v[44:45]
	v_mov_b32_e32 v65, v83
	v_mov_b32_e32 v69, v84
	v_mov_b32_e32 v59, v82
	v_mov_b32_e32 v57, v79
	v_pk_mov_b32 v[70:71], v[74:75], v[72:73] op_sel:[1,0]
	v_mov_b32_e32 v75, v73
	v_pk_add_f32 v[60:61], v[64:65], v[68:69]
	v_pk_add_f32 v[56:57], v[56:57], v[58:59]
	v_mul_f32_e32 v76, v49, v49
	v_mul_f32_e32 v78, v51, v51
	v_pk_add_f32 v[62:63], v[70:71], v[74:75]
	v_pk_add_f32 v[56:57], v[56:57], v[60:61]
	v_mul_f32_e32 v85, v0, v0
	v_mul_f32_e32 v86, v1, v1
	v_mul_f32_e32 v87, v2, v2
	v_mul_f32_e32 v88, v3, v3
	v_pk_fma_f32 v[72:73], v[48:49], v[48:49], v[76:77] op_sel_hi:[1,1,0]
	v_pk_fma_f32 v[76:77], v[50:51], v[50:51], v[78:79] op_sel_hi:[1,1,0]
	v_pk_add_f32 v[62:63], v[62:63], v[62:63] op_sel:[0,1] op_sel_hi:[1,0]
	v_pk_add_f32 v[56:57], v[56:57], v[56:57] op_sel:[0,1] op_sel_hi:[1,0]
	v_mov_b32_e32 v73, v87
	v_mov_b32_e32 v77, v88
	v_mov_b32_e32 v63, v86
	v_mov_b32_e32 v57, v85
	v_pk_add_f32 v[64:65], v[72:73], v[76:77]
	v_pk_add_f32 v[56:57], v[56:57], v[62:63]
	s_nop 0
	v_pk_add_f32 v[56:57], v[56:57], v[64:65]
	s_nop 0
	v_add_f32_e32 v56, v56, v57
	s_waitcnt lgkmcnt(0)
	s_nop 1
	v_add_f32_dpp v56, v56, v56 quad_perm:[1,0,3,2] row_mask:0xf bank_mask:0xf
	s_waitcnt lgkmcnt(0)
	s_nop 1
	v_add_f32_dpp v56, v56, v56 quad_perm:[2,3,0,1] row_mask:0xf bank_mask:0xf
	s_waitcnt lgkmcnt(0)
	s_nop 1
	v_add_f32_dpp v56, v56, v56 row_half_mirror row_mask:0xf bank_mask:0xf
	s_waitcnt lgkmcnt(0)
	s_nop 1
	v_add_f32_dpp v56, v56, v56 row_mirror row_mask:0xf bank_mask:0xf
	s_waitcnt lgkmcnt(0)
	v_mov_b32_e32 v57, v56
	s_nop 1
	v_permlane16_swap_b32_e32 v56, v57
	v_add_f32_e32 v56, v56, v57
	s_waitcnt lgkmcnt(0)
	v_mov_b32_e32 v57, v56
	s_nop 1
	v_permlane32_swap_b32_e32 v56, v57
	v_add_f32_e32 v56, v56, v57
	v_fmamk_f32 v56, v56, 0x3a000000, v30
	v_mul_f32_e32 v57, 0x4f800000, v56
	v_cmp_gt_f32_e32 vcc, s4, v56
	s_nop 1
	v_cndmask_b32_e32 v56, v56, v57, vcc
	v_sqrt_f32_e32 v57, v56
	s_nop 0
	v_add_u32_e32 v58, -1, v57
	v_add_u32_e32 v59, 1, v57
	v_fma_f32 v60, -v58, v57, v56
	v_fma_f32 v61, -v59, v57, v56
	v_cmp_ge_f32_e64 s[0:1], 0, v60
	s_nop 1
	v_cndmask_b32_e64 v57, v57, v58, s[0:1]
	v_cmp_lt_f32_e64 s[0:1], 0, v61
	s_nop 1
	v_cndmask_b32_e64 v57, v57, v59, s[0:1]
	v_mul_f32_e32 v58, 0x37800000, v57
	v_cndmask_b32_e32 v57, v57, v58, vcc
	v_cmp_class_f32_e32 vcc, v56, v31
	s_nop 1
	v_cndmask_b32_e32 v56, v57, v56, vcc
	v_div_scale_f32 v57, s[0:1], v56, v56, 1.0
	v_rcp_f32_e32 v58, v57
	v_div_scale_f32 v59, vcc, 1.0, v56, 1.0
	v_fma_f32 v60, -v57, v58, 1.0
	v_fmac_f32_e32 v58, v60, v58
	v_mul_f32_e32 v60, v59, v58
	v_fma_f32 v61, -v57, v60, v59
	v_fmac_f32_e32 v60, v61, v58
	v_fma_f32 v57, -v57, v60, v59
	v_div_fmas_f32 v57, v57, v58, v60
	v_div_fixup_f32 v56, v57, v56, 1.0
	v_pk_mul_f32 v[32:33], v[32:33], v[56:57] op_sel_hi:[1,0]
	v_pk_mul_f32 v[34:35], v[34:35], v[56:57] op_sel_hi:[1,0]
	v_pk_mul_f32 v[32:33], v[52:53], v[32:33]
	v_pk_mul_f32 v[34:35], v[54:55], v[34:35]
	global_store_dwordx4 v[22:23], v[32:35], off offset:-4096 nt
	s_nop 1
	v_pk_mul_f32 v[10:11], v[10:11], v[56:57] op_sel_hi:[1,0]
	v_pk_mul_f32 v[8:9], v[8:9], v[56:57] op_sel_hi:[1,0]
	v_pk_mul_f32 v[6:7], v[6:7], v[56:57] op_sel_hi:[1,0]
	v_pk_mul_f32 v[4:5], v[4:5], v[56:57] op_sel_hi:[1,0]
	v_pk_mul_f32 v[2:3], v[2:3], v[56:57] op_sel_hi:[1,0]
	v_pk_mul_f32 v[0:1], v[0:1], v[56:57] op_sel_hi:[1,0]
	v_pk_mul_f32 v[8:9], v[132:133], v[8:9]
	v_pk_mul_f32 v[10:11], v[134:135], v[10:11]
	global_store_dwordx4 v[22:23], v[8:11], off offset:-3072 nt
	s_nop 1
	v_pk_mul_f32 v[32:33], v[38:39], v[56:57] op_sel_hi:[1,0]
	v_pk_mul_f32 v[34:35], v[36:37], v[56:57] op_sel_hi:[1,0]
	v_pk_mul_f32 v[10:11], v[138:139], v[32:33]
	v_pk_mul_f32 v[8:9], v[136:137], v[34:35]
	global_store_dwordx4 v[22:23], v[8:11], off offset:-2048 nt
	s_nop 1
	v_pk_mul_f32 v[32:33], v[42:43], v[56:57] op_sel_hi:[1,0]
	v_pk_mul_f32 v[34:35], v[40:41], v[56:57] op_sel_hi:[1,0]
	v_pk_mul_f32 v[10:11], v[142:143], v[32:33]
	v_pk_mul_f32 v[8:9], v[140:141], v[34:35]
	global_store_dwordx4 v[22:23], v[8:11], off offset:-1024 nt
	s_nop 1
	v_pk_mul_f32 v[4:5], v[144:145], v[4:5]
	v_pk_mul_f32 v[6:7], v[146:147], v[6:7]
	global_store_dwordx4 v[22:23], v[4:7], off nt
	s_nop 1
	v_pk_mul_f32 v[8:9], v[46:47], v[56:57] op_sel_hi:[1,0]
	v_pk_mul_f32 v[10:11], v[44:45], v[56:57] op_sel_hi:[1,0]
	v_pk_mul_f32 v[6:7], v[150:151], v[8:9]
	v_pk_mul_f32 v[4:5], v[148:149], v[10:11]
	global_store_dwordx4 v[22:23], v[4:7], off offset:1024 nt
	s_nop 1
	v_pk_mul_f32 v[8:9], v[50:51], v[56:57] op_sel_hi:[1,0]
	v_pk_mul_f32 v[10:11], v[48:49], v[56:57] op_sel_hi:[1,0]
	v_pk_mul_f32 v[6:7], v[8:9], v[154:155]
	v_pk_mul_f32 v[4:5], v[10:11], v[152:153]
	global_store_dwordx4 v[22:23], v[4:7], off offset:2048 nt
	s_nop 1
	v_pk_mul_f32 v[0:1], v[0:1], v[156:157]
	v_pk_mul_f32 v[2:3], v[2:3], v[158:159]
	global_store_dwordx4 v[22:23], v[0:3], off offset:3072 nt
	v_lshl_add_u64 v[22:23], v[22:23], 0, s[2:3]
	s_cbranch_scc1 .LBB0_1762
